# nontemporal hint on the read-once f32 weight loads of the transpose items (P0 and the overlap slots), on top of the four-slot overlap
# baseline (speedup 1.0000x reference)
; #define LAS __attribute__((address_space(3)))
; __device__ __forceinline__ void transpose_item(const float* W, int ldw, const float* kgain, float scale, bf16_t* WT, int ldt, int k0, int n_src0, int n_dst0, LAS float* scr, int lane) {
;     float wv[32];
; #pragma unroll
;     for (int i = 0; i < 32; ++i) wv[i] = W[(size_t)(k0 + 2 * i + (lane >> 5)) * ldw + n_src0 + (lane & 31)];
;     if (kgain) {
; #pragma unroll
;         for (int i = 0; i < 32; ++i) wv[i] *= kgain[k0 + 2 * i + (lane >> 5)] * scale; }
; __device__ __forceinline__ void phase_prologue(const P& p, unsigned char* ws, LAS unsigned char* lds, int wg, int nwg) {
;     ...
;         transpose_item(p.w_plg + (size_t)l * D * D, D, nullptr, 1.f, (bf16_t*)(ws + WS_WPLG) + (size_t)l * D * D, D, (r / (D / 32)) * 64, (r % (D / 32)) * 32, (r % (D / 32)) * 32, scr, lane);
.LBB0_12:
	s_mov_b32 s33, 0xf2b9d649
	v_mul_hi_i32 v12, v68, s33
	v_add_u32_e32 v12, v12, v68
	v_lshrrev_b32_e32 v16, 31, v12
	v_ashrrev_i32_e32 v12, 15, v12
	v_add_u32_e32 v20, v12, v16
	v_mul_i32_i24_e32 v12, 0x8700, v20
	v_sub_u32_e32 v12, v68, v12
	s_movk_i32 s33, 0x2dff
	v_cmp_lt_i32_e32 vcc, s33, v12
	s_and_saveexec_b64 s[44:45], vcc
	s_xor_b64 s[80:81], exec, s[44:45]
	s_cbranch_execz .LBB0_40
	s_movk_i32 s33, 0x31ff
	v_cmp_lt_u32_e32 vcc, s33, v12
	s_and_saveexec_b64 s[44:45], vcc
	s_xor_b64 s[82:83], exec, s[44:45]
	s_cbranch_execz .LBB0_37
	s_movk_i32 s33, 0x35ff
	v_cmp_lt_u32_e32 vcc, s33, v12
	s_and_saveexec_b64 s[44:45], vcc
	s_xor_b64 s[84:85], exec, s[44:45]
	s_cbranch_execz .LBB0_34
	s_movk_i32 s33, 0x3dff
	v_cmp_lt_u32_e32 vcc, s33, v12
	s_and_saveexec_b64 s[44:45], vcc
	s_xor_b64 s[86:87], exec, s[44:45]
	s_cbranch_execz .LBB0_31
	s_movk_i32 s33, 0x5dff
	v_cmp_lt_u32_e32 vcc, s33, v12
	v_ashrrev_i32_e32 v21, 31, v20
	s_and_saveexec_b64 s[44:45], vcc
	s_xor_b64 s[88:89], exec, s[44:45]
	s_cbranch_execz .LBB0_26
	s_movk_i32 s33, 0x7dff
	v_cmp_lt_u32_e32 vcc, s33, v12
	s_and_saveexec_b64 s[44:45], vcc
	s_xor_b64 s[90:91], exec, s[44:45]
	s_cbranch_execz .LBB0_23
	s_movk_i32 s33, 0x7eff
	v_cmp_lt_u32_e32 vcc, s33, v12
	s_and_saveexec_b64 s[44:45], vcc
	s_xor_b64 s[44:45], exec, s[44:45]
	s_cbranch_execz .LBB0_20
	v_lshlrev_b64 v[16:17], 24, v[20:21]
	v_lshl_add_u64 v[18:19], s[52:53], 0, v[16:17]
	v_and_b32_e32 v16, 0x7fffffc0, v12
	v_lshlrev_b32_e32 v12, 5, v12
	v_and_b32_e32 v40, 0x7e0, v12
	v_add_u32_e32 v16, 0xffff8100, v16
	v_lshlrev_b32_e32 v12, 2, v40
	v_or_b32_e32 v22, v16, v8
	v_lshl_add_u64 v[18:19], v[18:19], 0, v[12:13]
	v_lshlrev_b32_e32 v12, 2, v10
	v_lshl_add_u64 v[18:19], v[18:19], 0, v[12:13]
	v_or_b32_e32 v12, 2, v22
	v_lshlrev_b64 v[26:27], 13, v[12:13]
	v_or_b32_e32 v12, 4, v22
	v_lshlrev_b64 v[28:29], 13, v[12:13]
	v_or_b32_e32 v12, 6, v22
	v_lshlrev_b64 v[30:31], 13, v[12:13]
	v_or_b32_e32 v12, 8, v22
	v_lshlrev_b64 v[32:33], 13, v[12:13]
	v_or_b32_e32 v12, 10, v22
	v_mov_b32_e32 v23, v13
	v_lshlrev_b64 v[34:35], 13, v[12:13]
	v_or_b32_e32 v12, 12, v22
	v_lshlrev_b64 v[24:25], 13, v[22:23]
	v_lshlrev_b64 v[36:37], 13, v[12:13]
	v_or_b32_e32 v12, 14, v22
	v_lshl_add_u64 v[24:25], v[18:19], 0, v[24:25]
	v_lshlrev_b64 v[38:39], 13, v[12:13]
	v_or_b32_e32 v12, 16, v22
	v_lshl_add_u64 v[26:27], v[18:19], 0, v[26:27]
	v_lshl_add_u64 v[28:29], v[18:19], 0, v[28:29]
	v_lshl_add_u64 v[30:31], v[18:19], 0, v[30:31]
	v_lshl_add_u64 v[32:33], v[18:19], 0, v[32:33]
	v_lshl_add_u64 v[34:35], v[18:19], 0, v[34:35]
	v_lshl_add_u64 v[36:37], v[18:19], 0, v[36:37]
	v_lshl_add_u64 v[38:39], v[18:19], 0, v[38:39]
	global_load_dword v17, v[24:25], off nt
	global_load_dword v41, v[26:27], off nt
	global_load_dword v42, v[28:29], off nt
	global_load_dword v43, v[30:31], off nt
	global_load_dword v44, v[32:33], off nt
	global_load_dword v45, v[34:35], off nt
	global_load_dword v46, v[36:37], off nt
	global_load_dword v47, v[38:39], off nt
	v_lshlrev_b64 v[24:25], 13, v[12:13]
	v_or_b32_e32 v12, 18, v22
	v_lshlrev_b64 v[26:27], 13, v[12:13]
	v_or_b32_e32 v12, 20, v22
	v_lshlrev_b64 v[28:29], 13, v[12:13]
	v_or_b32_e32 v12, 22, v22
	v_lshlrev_b64 v[30:31], 13, v[12:13]
	v_or_b32_e32 v12, 24, v22
	v_lshlrev_b64 v[32:33], 13, v[12:13]
	v_or_b32_e32 v12, 26, v22
	v_lshlrev_b64 v[34:35], 13, v[12:13]
	v_or_b32_e32 v12, 28, v22
	v_lshlrev_b64 v[36:37], 13, v[12:13]
	v_or_b32_e32 v12, 30, v22
	v_lshl_add_u64 v[24:25], v[18:19], 0, v[24:25]
	v_lshlrev_b64 v[38:39], 13, v[12:13]
	v_or_b32_e32 v12, 32, v22
	v_lshl_add_u64 v[26:27], v[18:19], 0, v[26:27]
	v_lshl_add_u64 v[28:29], v[18:19], 0, v[28:29]
	v_lshl_add_u64 v[30:31], v[18:19], 0, v[30:31]
	v_lshl_add_u64 v[32:33], v[18:19], 0, v[32:33]
	v_lshl_add_u64 v[34:35], v[18:19], 0, v[34:35]
	v_lshl_add_u64 v[36:37], v[18:19], 0, v[36:37]
	v_lshl_add_u64 v[38:39], v[18:19], 0, v[38:39]
	global_load_dword v48, v[24:25], off nt
	global_load_dword v49, v[26:27], off nt
	global_load_dword v50, v[28:29], off nt
	global_load_dword v51, v[30:31], off nt
	global_load_dword v52, v[32:33], off nt
	global_load_dword v53, v[34:35], off nt
	global_load_dword v54, v[36:37], off nt
	global_load_dword v55, v[38:39], off nt
	v_lshlrev_b64 v[24:25], 13, v[12:13]
	v_or_b32_e32 v12, 34, v22
	v_lshlrev_b64 v[26:27], 13, v[12:13]
	v_or_b32_e32 v12, 36, v22
	v_lshlrev_b64 v[28:29], 13, v[12:13]
	v_or_b32_e32 v12, 38, v22
	v_lshlrev_b64 v[30:31], 13, v[12:13]
	v_or_b32_e32 v12, 40, v22
	v_lshlrev_b64 v[32:33], 13, v[12:13]
	v_or_b32_e32 v12, 42, v22
	v_lshlrev_b64 v[34:35], 13, v[12:13]
	v_or_b32_e32 v12, 44, v22
	v_lshlrev_b64 v[36:37], 13, v[12:13]
	v_or_b32_e32 v12, 46, v22
	v_lshlrev_b64 v[38:39], 13, v[12:13]
	v_lshl_add_u64 v[24:25], v[18:19], 0, v[24:25]
	v_lshl_add_u64 v[38:39], v[18:19], 0, v[38:39]
	v_or_b32_e32 v12, 48, v22
	v_lshl_add_u64 v[26:27], v[18:19], 0, v[26:27]
	v_lshl_add_u64 v[28:29], v[18:19], 0, v[28:29]
	v_lshl_add_u64 v[30:31], v[18:19], 0, v[30:31]
	v_lshl_add_u64 v[32:33], v[18:19], 0, v[32:33]
	v_lshl_add_u64 v[34:35], v[18:19], 0, v[34:35]
	v_lshl_add_u64 v[36:37], v[18:19], 0, v[36:37]
	global_load_dword v69, v[24:25], off nt
	global_load_dword v70, v[26:27], off nt
	global_load_dword v71, v[28:29], off nt
	global_load_dword v72, v[30:31], off nt
	global_load_dword v73, v[32:33], off nt
	global_load_dword v74, v[34:35], off nt
	global_load_dword v75, v[36:37], off nt
	s_nop 0
	global_load_dword v38, v[38:39], off nt
	v_lshlrev_b64 v[24:25], 13, v[12:13]
	v_or_b32_e32 v12, 50, v22
	v_lshlrev_b64 v[26:27], 13, v[12:13]
	v_or_b32_e32 v12, 52, v22
	v_lshlrev_b64 v[28:29], 13, v[12:13]
	v_or_b32_e32 v12, 54, v22
	v_lshlrev_b64 v[30:31], 13, v[12:13]
	v_or_b32_e32 v12, 56, v22
	v_lshlrev_b64 v[32:33], 13, v[12:13]
	v_or_b32_e32 v12, 58, v22
	v_lshlrev_b64 v[34:35], 13, v[12:13]
	v_or_b32_e32 v12, 60, v22
	v_lshlrev_b64 v[36:37], 13, v[12:13]
	v_or_b32_e32 v12, 62, v22
	v_lshl_add_u64 v[24:25], v[18:19], 0, v[24:25]
	v_lshl_add_u64 v[26:27], v[18:19], 0, v[26:27]
	v_lshl_add_u64 v[28:29], v[18:19], 0, v[28:29]
	v_lshlrev_b64 v[22:23], 13, v[12:13]
	v_lshl_add_u64 v[30:31], v[18:19], 0, v[30:31]
	v_lshl_add_u64 v[32:33], v[18:19], 0, v[32:33]
	v_lshl_add_u64 v[34:35], v[18:19], 0, v[34:35]
	v_lshl_add_u64 v[36:37], v[18:19], 0, v[36:37]
	v_lshl_add_u64 v[18:19], v[18:19], 0, v[22:23]
	global_load_dword v12, v[24:25], off nt
	global_load_dword v22, v[26:27], off nt
	global_load_dword v23, v[28:29], off nt
	s_nop 0
	global_load_dword v24, v[30:31], off nt
	global_load_dword v25, v[32:33], off nt
	global_load_dword v26, v[34:35], off nt
	global_load_dword v27, v[36:37], off nt
	global_load_dword v28, v[18:19], off nt
	s_waitcnt vmcnt(30)
; #define LAS __attribute__((address_space(3)))
; __device__ __forceinline__ unsigned pk2(float lo, float hi) { return pg8::cvt_pk_bf16(lo, hi); }
; __device__ __forceinline__ void transpose_item(const float* W, int ldw, const float* kgain, float scale, bf16_t* WT, int ldt, int k0, int n_src0, int n_dst0, LAS float* scr, int lane) {
;     ...
; #pragma unroll
;     for (int i = 0; i < 32; ++i) scr[(2 * i + (lane >> 5)) * 33 + (lane & 31)] = wv[i];
;     asm volatile("s_waitcnt lgkmcnt(0)" ::: "memory");
;     const int c = lane & 7;
; #pragma unroll
;     for (int j = 0; j < 4; ++j) { const int n = (lane >> 3) + 8 * j; const LAS float* s = scr + (8 * c) * 33 + n;
;         u32x4 o; o.x = pk2(s[0 * 33], s[1 * 33]); o.y = pk2(s[2 * 33], s[3 * 33]); o.z = pk2(s[4 * 33], s[5 * 33]); o.w = pk2(s[6 * 33], s[7 * 33]);
;         *(u32x4*)(WT + (size_t)(n_dst0 + n) * ldt + k0 + 8 * c) = o; }
;     asm volatile("s_waitcnt lgkmcnt(0)" ::: "memory");
; }
; __device__ __forceinline__ void phase_prologue(const P& p, unsigned char* ws, LAS unsigned char* lds, int wg, int nwg) {
;     ...
;         if (r < I_PL) { transpose_item(p.w_ple + (size_t)l * PLE * D, D, nullptr, 1.f, (bf16_t*)(ws + WS_WPLE) + (size_t)l * D * PLE, PLE, (r / (D / 32)) * 64, (r % (D / 32)) * 32, (r % (D / 32)) * 32, scr, lane); continue; } r -= I_PL;
	ds_write2_b32 v5, v17, v41 offset1:66
	s_waitcnt vmcnt(28)
	ds_write2_b32 v5, v42, v43 offset0:132 offset1:198
	v_add_u32_e32 v17, 0x400, v5
	s_waitcnt vmcnt(26)
	ds_write2_b32 v17, v44, v45 offset0:8 offset1:74
	s_waitcnt vmcnt(24)
	ds_write2_b32 v17, v46, v47 offset0:140 offset1:206
	v_add_u32_e32 v17, 0x800, v5
	s_waitcnt vmcnt(22)
	ds_write2_b32 v17, v48, v49 offset0:16 offset1:82
	s_waitcnt vmcnt(20)
	ds_write2_b32 v17, v50, v51 offset0:148 offset1:214
	v_add_u32_e32 v17, 0xc00, v5
	s_waitcnt vmcnt(18)
	ds_write2_b32 v17, v52, v53 offset0:24 offset1:90
	s_waitcnt vmcnt(16)
	ds_write2_b32 v17, v54, v55 offset0:156 offset1:222
	v_add_u32_e32 v17, 0x1000, v5
	s_waitcnt vmcnt(14)
	ds_write2_b32 v17, v69, v70 offset0:32 offset1:98
	s_waitcnt vmcnt(12)
	ds_write2_b32 v17, v71, v72 offset0:164 offset1:230
	v_add_u32_e32 v17, 0x1400, v5
	s_waitcnt vmcnt(10)
	ds_write2_b32 v17, v73, v74 offset0:40 offset1:106
	s_waitcnt vmcnt(8)
	ds_write2_b32 v17, v75, v38 offset0:172 offset1:238
	v_add_u32_e32 v17, 0x1800, v5
	s_waitcnt vmcnt(6)
	ds_write2_b32 v17, v12, v22 offset0:48 offset1:114
	s_waitcnt vmcnt(4)
	ds_write2_b32 v17, v23, v24 offset0:180 offset1:246
	v_add_u32_e32 v12, 0x1c00, v5
	s_waitcnt vmcnt(2)
	ds_write2_b32 v12, v25, v26 offset0:56 offset1:122
	s_waitcnt vmcnt(0)
	ds_write2_b32 v12, v27, v28 offset0:188 offset1:254
	s_waitcnt lgkmcnt(0)
	v_lshlrev_b64 v[18:19], 23, v[20:21]
	ds_read2_b32 v[20:21], v11 offset0:33 offset1:41
	ds_read2_b32 v[22:23], v11 offset1:8
	ds_read2_b32 v[24:25], v11 offset0:66 offset1:74
	ds_read2_b32 v[26:27], v11 offset0:99 offset1:107
	ds_read2_b32 v[28:29], v11 offset0:132 offset1:140
	ds_read2_b32 v[30:31], v11 offset0:165 offset1:173
	ds_read2_b32 v[32:33], v11 offset0:198 offset1:206
	ds_read2_b32 v[34:35], v11 offset0:231 offset1:239
	v_lshl_add_u64 v[18:19], s[56:57], 0, v[18:19]
	v_mov_b32_e32 v17, v13
	v_lshl_add_u64 v[16:17], v[16:17], 1, v[18:19]
	v_lshlrev_b32_e32 v12, 1, v14
	v_lshl_add_u64 v[36:37], v[16:17], 0, v[12:13]
	v_or_b32_e32 v12, v40, v7
	v_lshlrev_b32_e32 v12, 12, v12
	s_waitcnt lgkmcnt(6)
	v_cvt_pk_bf16_f32 v16, v22, v20
	s_waitcnt lgkmcnt(4)
	v_cvt_pk_bf16_f32 v17, v24, v26
	s_waitcnt lgkmcnt(2)
	v_cvt_pk_bf16_f32 v18, v28, v30
	s_waitcnt lgkmcnt(0)
	v_cvt_pk_bf16_f32 v19, v32, v34
	v_lshl_add_u64 v[38:39], v[36:37], 0, v[12:13]
	global_store_dwordx4 v[38:39], v[16:19], off
	v_or_b32_e32 v12, v40, v15
	v_lshlrev_b32_e32 v12, 12, v12
	v_cvt_pk_bf16_f32 v16, v23, v21
	v_cvt_pk_bf16_f32 v17, v25, v27
	v_cvt_pk_bf16_f32 v18, v29, v31
	v_cvt_pk_bf16_f32 v19, v33, v35
	ds_read2_b32 v[22:23], v11 offset0:49 offset1:57
	ds_read2_b32 v[24:25], v11 offset0:16 offset1:24
	ds_read2_b32 v[26:27], v11 offset0:82 offset1:90
	ds_read2_b32 v[28:29], v11 offset0:115 offset1:123
	ds_read2_b32 v[30:31], v11 offset0:148 offset1:156
	ds_read2_b32 v[32:33], v11 offset0:181 offset1:189
	ds_read2_b32 v[34:35], v11 offset0:214 offset1:222
	ds_read2_b32 v[38:39], v11 offset0:247 offset1:255
	v_lshl_add_u64 v[20:21], v[36:37], 0, v[12:13]
	v_or_b32_e32 v12, v40, v56
	v_lshlrev_b32_e32 v12, 12, v12
	global_store_dwordx4 v[20:21], v[16:19], off
	v_lshl_add_u64 v[20:21], v[36:37], 0, v[12:13]
	v_or_b32_e32 v12, v40, v57
	s_waitcnt lgkmcnt(6)
	v_cvt_pk_bf16_f32 v16, v24, v22
	s_waitcnt lgkmcnt(4)
	v_cvt_pk_bf16_f32 v17, v26, v28
	s_waitcnt lgkmcnt(2)
	v_cvt_pk_bf16_f32 v18, v30, v32
	s_waitcnt lgkmcnt(0)
	v_cvt_pk_bf16_f32 v19, v34, v38
	v_lshlrev_b32_e32 v12, 12, v12
	global_store_dwordx4 v[20:21], v[16:19], off
	v_lshl_add_u64 v[20:21], v[36:37], 0, v[12:13]
	s_nop 0
	v_cvt_pk_bf16_f32 v16, v25, v23
	v_cvt_pk_bf16_f32 v17, v27, v29
	v_cvt_pk_bf16_f32 v18, v31, v33
	v_cvt_pk_bf16_f32 v19, v35, v39
	global_store_dwordx4 v[20:21], v[16:19], off
	s_waitcnt lgkmcnt(0)
.LBB0_20:
	s_andn2_saveexec_b64 s[44:45], s[44:45]
	s_cbranch_execz .LBB0_22
	v_lshlrev_b64 v[16:17], 21, v[20:21]
	v_lshl_add_u64 v[18:19], s[48:49], 0, v[16:17]
	v_and_b32_e32 v16, 0x7fc0, v12
	v_lshlrev_b32_e32 v12, 5, v12
	v_and_b32_e32 v40, 0x7e0, v12
	v_add_u32_e32 v16, 0xffff8200, v16
	v_lshlrev_b32_e32 v12, 2, v40
	v_or_b32_e32 v22, v16, v8
	v_lshl_add_u64 v[18:19], v[18:19], 0, v[12:13]
	v_lshlrev_b32_e32 v12, 2, v10
	v_lshl_add_u64 v[18:19], v[18:19], 0, v[12:13]
	v_or_b32_e32 v12, 2, v22
	v_lshlrev_b64 v[26:27], 13, v[12:13]
	v_or_b32_e32 v12, 4, v22
	v_lshlrev_b64 v[28:29], 13, v[12:13]
	v_or_b32_e32 v12, 6, v22
	v_lshlrev_b64 v[30:31], 13, v[12:13]
	v_or_b32_e32 v12, 8, v22
	v_lshlrev_b64 v[32:33], 13, v[12:13]
	v_or_b32_e32 v12, 10, v22
	v_mov_b32_e32 v23, v13
	v_lshlrev_b64 v[34:35], 13, v[12:13]
	v_or_b32_e32 v12, 12, v22
	v_lshlrev_b64 v[24:25], 13, v[22:23]
	v_lshlrev_b64 v[36:37], 13, v[12:13]
	v_or_b32_e32 v12, 14, v22
	v_lshl_add_u64 v[24:25], v[18:19], 0, v[24:25]
	v_lshlrev_b64 v[38:39], 13, v[12:13]
	v_or_b32_e32 v12, 16, v22
	v_lshl_add_u64 v[26:27], v[18:19], 0, v[26:27]
	v_lshl_add_u64 v[28:29], v[18:19], 0, v[28:29]
	v_lshl_add_u64 v[30:31], v[18:19], 0, v[30:31]
	v_lshl_add_u64 v[32:33], v[18:19], 0, v[32:33]
	v_lshl_add_u64 v[34:35], v[18:19], 0, v[34:35]
	v_lshl_add_u64 v[36:37], v[18:19], 0, v[36:37]
	v_lshl_add_u64 v[38:39], v[18:19], 0, v[38:39]
	global_load_dword v17, v[24:25], off nt
	global_load_dword v41, v[26:27], off nt
	global_load_dword v42, v[28:29], off nt
	global_load_dword v43, v[30:31], off nt
	global_load_dword v44, v[32:33], off nt
	global_load_dword v45, v[34:35], off nt
	global_load_dword v46, v[36:37], off nt
	global_load_dword v47, v[38:39], off nt
	v_lshlrev_b64 v[24:25], 13, v[12:13]
	v_or_b32_e32 v12, 18, v22
	v_lshlrev_b64 v[26:27], 13, v[12:13]
	v_or_b32_e32 v12, 20, v22
; __device__ __forceinline__ void transpose_item(const float* W, int ldw, const float* kgain, float scale, bf16_t* WT, int ldt, int k0, int n_src0, int n_dst0, LAS float* scr, int lane) {
;     float wv[32];
; #pragma unroll
;     for (int i = 0; i < 32; ++i) wv[i] = W[(size_t)(k0 + 2 * i + (lane >> 5)) * ldw + n_src0 + (lane & 31)];
	v_lshlrev_b64 v[28:29], 13, v[12:13]
	v_or_b32_e32 v12, 22, v22
	v_lshlrev_b64 v[30:31], 13, v[12:13]
	v_or_b32_e32 v12, 24, v22
	v_lshlrev_b64 v[32:33], 13, v[12:13]
	v_or_b32_e32 v12, 26, v22
	v_lshlrev_b64 v[34:35], 13, v[12:13]
	v_or_b32_e32 v12, 28, v22
	v_lshlrev_b64 v[36:37], 13, v[12:13]
	v_or_b32_e32 v12, 30, v22
	v_lshl_add_u64 v[24:25], v[18:19], 0, v[24:25]
	v_lshlrev_b64 v[38:39], 13, v[12:13]
	v_or_b32_e32 v12, 32, v22
	v_lshl_add_u64 v[26:27], v[18:19], 0, v[26:27]
	v_lshl_add_u64 v[28:29], v[18:19], 0, v[28:29]
	v_lshl_add_u64 v[30:31], v[18:19], 0, v[30:31]
	v_lshl_add_u64 v[32:33], v[18:19], 0, v[32:33]
	v_lshl_add_u64 v[34:35], v[18:19], 0, v[34:35]
	v_lshl_add_u64 v[36:37], v[18:19], 0, v[36:37]
	v_lshl_add_u64 v[38:39], v[18:19], 0, v[38:39]
	global_load_dword v48, v[24:25], off nt
	global_load_dword v49, v[26:27], off nt
	global_load_dword v50, v[28:29], off nt
	global_load_dword v51, v[30:31], off nt
	global_load_dword v52, v[32:33], off nt
	global_load_dword v53, v[34:35], off nt
	global_load_dword v54, v[36:37], off nt
	global_load_dword v55, v[38:39], off nt
	v_lshlrev_b64 v[24:25], 13, v[12:13]
	v_or_b32_e32 v12, 34, v22
	v_lshlrev_b64 v[26:27], 13, v[12:13]
	v_or_b32_e32 v12, 36, v22
	v_lshlrev_b64 v[28:29], 13, v[12:13]
	v_or_b32_e32 v12, 38, v22
	v_lshlrev_b64 v[30:31], 13, v[12:13]
	v_or_b32_e32 v12, 40, v22
	v_lshlrev_b64 v[32:33], 13, v[12:13]
	v_or_b32_e32 v12, 42, v22
	v_lshlrev_b64 v[34:35], 13, v[12:13]
	v_or_b32_e32 v12, 44, v22
	v_lshlrev_b64 v[36:37], 13, v[12:13]
	v_or_b32_e32 v12, 46, v22
	v_lshlrev_b64 v[38:39], 13, v[12:13]
	v_lshl_add_u64 v[24:25], v[18:19], 0, v[24:25]
	v_lshl_add_u64 v[38:39], v[18:19], 0, v[38:39]
	v_or_b32_e32 v12, 48, v22
	v_lshl_add_u64 v[26:27], v[18:19], 0, v[26:27]
	v_lshl_add_u64 v[28:29], v[18:19], 0, v[28:29]
	v_lshl_add_u64 v[30:31], v[18:19], 0, v[30:31]
	v_lshl_add_u64 v[32:33], v[18:19], 0, v[32:33]
	v_lshl_add_u64 v[34:35], v[18:19], 0, v[34:35]
	v_lshl_add_u64 v[36:37], v[18:19], 0, v[36:37]
	global_load_dword v69, v[24:25], off nt
	global_load_dword v70, v[26:27], off nt
	global_load_dword v71, v[28:29], off nt
	global_load_dword v72, v[30:31], off nt
	global_load_dword v73, v[32:33], off nt
	global_load_dword v74, v[34:35], off nt
	global_load_dword v75, v[36:37], off nt
	s_nop 0
	global_load_dword v38, v[38:39], off nt
	v_lshlrev_b64 v[24:25], 13, v[12:13]
	v_or_b32_e32 v12, 50, v22
	v_lshlrev_b64 v[26:27], 13, v[12:13]
	v_or_b32_e32 v12, 52, v22
	v_lshlrev_b64 v[28:29], 13, v[12:13]
	v_or_b32_e32 v12, 54, v22
	v_lshlrev_b64 v[30:31], 13, v[12:13]
	v_or_b32_e32 v12, 56, v22
	v_lshlrev_b64 v[32:33], 13, v[12:13]
	v_or_b32_e32 v12, 58, v22
	v_lshlrev_b64 v[34:35], 13, v[12:13]
	v_or_b32_e32 v12, 60, v22
	v_lshlrev_b64 v[36:37], 13, v[12:13]
	v_or_b32_e32 v12, 62, v22
	v_lshl_add_u64 v[24:25], v[18:19], 0, v[24:25]
	v_lshl_add_u64 v[26:27], v[18:19], 0, v[26:27]
	v_lshl_add_u64 v[28:29], v[18:19], 0, v[28:29]
	v_lshlrev_b64 v[22:23], 13, v[12:13]
	v_lshl_add_u64 v[30:31], v[18:19], 0, v[30:31]
	v_lshl_add_u64 v[32:33], v[18:19], 0, v[32:33]
	v_lshl_add_u64 v[34:35], v[18:19], 0, v[34:35]
	v_lshl_add_u64 v[36:37], v[18:19], 0, v[36:37]
	v_lshl_add_u64 v[18:19], v[18:19], 0, v[22:23]
	global_load_dword v12, v[24:25], off nt
	global_load_dword v22, v[26:27], off nt
	global_load_dword v23, v[28:29], off nt
	s_nop 0
	global_load_dword v24, v[30:31], off nt
	global_load_dword v25, v[32:33], off nt
	global_load_dword v26, v[34:35], off nt
	global_load_dword v27, v[36:37], off nt
	global_load_dword v28, v[18:19], off nt
	s_waitcnt vmcnt(30)
	ds_write2_b32 v5, v17, v41 offset1:66
	s_waitcnt vmcnt(28)
; #define LAS __attribute__((address_space(3)))
; __device__ __forceinline__ unsigned pk2(float lo, float hi) { return pg8::cvt_pk_bf16(lo, hi); }
; __device__ __forceinline__ void transpose_item(const float* W, int ldw, const float* kgain, float scale, bf16_t* WT, int ldt, int k0, int n_src0, int n_dst0, LAS float* scr, int lane) {
;     ...
; #pragma unroll
;     for (int i = 0; i < 32; ++i) scr[(2 * i + (lane >> 5)) * 33 + (lane & 31)] = wv[i];
;     asm volatile("s_waitcnt lgkmcnt(0)" ::: "memory");
;     const int c = lane & 7;
; #pragma unroll
;     for (int j = 0; j < 4; ++j) { const int n = (lane >> 3) + 8 * j; const LAS float* s = scr + (8 * c) * 33 + n;
;         u32x4 o; o.x = pk2(s[0 * 33], s[1 * 33]); o.y = pk2(s[2 * 33], s[3 * 33]); o.z = pk2(s[4 * 33], s[5 * 33]); o.w = pk2(s[6 * 33], s[7 * 33]);
;         *(u32x4*)(WT + (size_t)(n_dst0 + n) * ldt + k0 + 8 * c) = o; }
;     asm volatile("s_waitcnt lgkmcnt(0)" ::: "memory");
; }
	ds_write2_b32 v5, v42, v43 offset0:132 offset1:198
	v_add_u32_e32 v17, 0x400, v5
	s_waitcnt vmcnt(26)
	ds_write2_b32 v17, v44, v45 offset0:8 offset1:74
	s_waitcnt vmcnt(24)
	ds_write2_b32 v17, v46, v47 offset0:140 offset1:206
	v_add_u32_e32 v17, 0x800, v5
	s_waitcnt vmcnt(22)
	ds_write2_b32 v17, v48, v49 offset0:16 offset1:82
	s_waitcnt vmcnt(20)
	ds_write2_b32 v17, v50, v51 offset0:148 offset1:214
	v_add_u32_e32 v17, 0xc00, v5
	s_waitcnt vmcnt(18)
	ds_write2_b32 v17, v52, v53 offset0:24 offset1:90
	s_waitcnt vmcnt(16)
	ds_write2_b32 v17, v54, v55 offset0:156 offset1:222
	v_add_u32_e32 v17, 0x1000, v5
	s_waitcnt vmcnt(14)
	ds_write2_b32 v17, v69, v70 offset0:32 offset1:98
	s_waitcnt vmcnt(12)
	ds_write2_b32 v17, v71, v72 offset0:164 offset1:230
	v_add_u32_e32 v17, 0x1400, v5
	s_waitcnt vmcnt(10)
	ds_write2_b32 v17, v73, v74 offset0:40 offset1:106
	s_waitcnt vmcnt(8)
	ds_write2_b32 v17, v75, v38 offset0:172 offset1:238
	v_add_u32_e32 v17, 0x1800, v5
	s_waitcnt vmcnt(6)
	ds_write2_b32 v17, v12, v22 offset0:48 offset1:114
	s_waitcnt vmcnt(4)
	ds_write2_b32 v17, v23, v24 offset0:180 offset1:246
	v_add_u32_e32 v12, 0x1c00, v5
	s_waitcnt vmcnt(2)
	ds_write2_b32 v12, v25, v26 offset0:56 offset1:122
	s_waitcnt vmcnt(0)
	ds_write2_b32 v12, v27, v28 offset0:188 offset1:254
	s_waitcnt lgkmcnt(0)
	v_lshlrev_b64 v[18:19], 20, v[20:21]
	ds_read2_b32 v[20:21], v11 offset0:33 offset1:41
	ds_read2_b32 v[22:23], v11 offset1:8
	ds_read2_b32 v[24:25], v11 offset0:66 offset1:74
	ds_read2_b32 v[26:27], v11 offset0:99 offset1:107
	ds_read2_b32 v[28:29], v11 offset0:132 offset1:140
	ds_read2_b32 v[30:31], v11 offset0:165 offset1:173
	ds_read2_b32 v[32:33], v11 offset0:198 offset1:206
	ds_read2_b32 v[34:35], v11 offset0:231 offset1:239
	v_lshl_add_u64 v[18:19], s[58:59], 0, v[18:19]
	v_mov_b32_e32 v17, v13
	v_lshl_add_u64 v[16:17], v[16:17], 1, v[18:19]
	v_lshlrev_b32_e32 v12, 1, v14
	v_lshl_add_u64 v[36:37], v[16:17], 0, v[12:13]
	v_or_b32_e32 v12, v40, v7
	v_lshlrev_b32_e32 v12, 9, v12
	s_waitcnt lgkmcnt(6)
	v_cvt_pk_bf16_f32 v16, v22, v20
	s_waitcnt lgkmcnt(4)
	v_cvt_pk_bf16_f32 v17, v24, v26
	s_waitcnt lgkmcnt(2)
	v_cvt_pk_bf16_f32 v18, v28, v30
	s_waitcnt lgkmcnt(0)
	v_cvt_pk_bf16_f32 v19, v32, v34
	v_lshl_add_u64 v[38:39], v[36:37], 0, v[12:13]
	global_store_dwordx4 v[38:39], v[16:19], off
	v_or_b32_e32 v12, v40, v15
	v_lshlrev_b32_e32 v12, 9, v12
	v_cvt_pk_bf16_f32 v16, v23, v21
	v_cvt_pk_bf16_f32 v17, v25, v27
	v_cvt_pk_bf16_f32 v18, v29, v31
	v_cvt_pk_bf16_f32 v19, v33, v35
	ds_read2_b32 v[22:23], v11 offset0:49 offset1:57
	ds_read2_b32 v[24:25], v11 offset0:16 offset1:24
	ds_read2_b32 v[26:27], v11 offset0:82 offset1:90
	ds_read2_b32 v[28:29], v11 offset0:115 offset1:123
	ds_read2_b32 v[30:31], v11 offset0:148 offset1:156
	ds_read2_b32 v[32:33], v11 offset0:181 offset1:189
	ds_read2_b32 v[34:35], v11 offset0:214 offset1:222
	ds_read2_b32 v[38:39], v11 offset0:247 offset1:255
	v_lshl_add_u64 v[20:21], v[36:37], 0, v[12:13]
	v_or_b32_e32 v12, v40, v56
	v_lshlrev_b32_e32 v12, 9, v12
	global_store_dwordx4 v[20:21], v[16:19], off
	v_lshl_add_u64 v[20:21], v[36:37], 0, v[12:13]
	v_or_b32_e32 v12, v40, v57
	s_waitcnt lgkmcnt(6)
	v_cvt_pk_bf16_f32 v16, v24, v22
	s_waitcnt lgkmcnt(4)
	v_cvt_pk_bf16_f32 v17, v26, v28
	s_waitcnt lgkmcnt(2)
	v_cvt_pk_bf16_f32 v18, v30, v32
	s_waitcnt lgkmcnt(0)
	v_cvt_pk_bf16_f32 v19, v34, v38
	v_lshlrev_b32_e32 v12, 9, v12
	global_store_dwordx4 v[20:21], v[16:19], off
	v_lshl_add_u64 v[20:21], v[36:37], 0, v[12:13]
	s_nop 0
	v_cvt_pk_bf16_f32 v16, v25, v23
	v_cvt_pk_bf16_f32 v17, v27, v29
	v_cvt_pk_bf16_f32 v18, v31, v33
	v_cvt_pk_bf16_f32 v19, v35, v39
	global_store_dwordx4 v[20:21], v[16:19], off
	s_waitcnt lgkmcnt(0)

; __device__ __forceinline__ void transpose_item(const float* W, int ldw, const float* kgain, float scale, bf16_t* WT, int ldt, int k0, int n_src0, int n_dst0, LAS float* scr, int lane) {
;     float wv[32];
; #pragma unroll
;     for (int i = 0; i < 32; ++i) wv[i] = W[(size_t)(k0 + 2 * i + (lane >> 5)) * ldw + n_src0 + (lane & 31)];
; __device__ __forceinline__ void phase_prologue(const P& p, unsigned char* ws, LAS unsigned char* lds, int wg, int nwg) {
;     ...
;         if (r < I_F2) { transpose_item(p.w_ff2 + (size_t)l * DFF * D, D, nullptr, 1.f, (bf16_t*)(ws + WS_WFF2) + (size_t)l * D * DFF, DFF, (r / (D / 32)) * 64, (r % (D / 32)) * 32, (r % (D / 32)) * 32, scr, lane); continue; } r -= I_F2;
.LBB0_23:
	s_andn2_saveexec_b64 s[44:45], s[90:91]
	s_cbranch_execz .LBB0_25
	v_lshlrev_b64 v[16:17], 26, v[20:21]
	v_lshl_add_u64 v[18:19], s[46:47], 0, v[16:17]
	v_and_b32_e32 v16, 0x7fc0, v12
	v_lshlrev_b32_e32 v12, 5, v12
	v_and_b32_e32 v40, 0x7e0, v12
	v_add_u32_e32 v16, 0xffffa200, v16
	v_lshlrev_b32_e32 v12, 2, v40
	v_or_b32_e32 v22, v16, v8
	v_lshl_add_u64 v[18:19], v[18:19], 0, v[12:13]
	v_lshlrev_b32_e32 v12, 2, v10
	v_lshl_add_u64 v[18:19], v[18:19], 0, v[12:13]
	v_or_b32_e32 v12, 2, v22
	v_lshlrev_b64 v[26:27], 13, v[12:13]
	v_or_b32_e32 v12, 4, v22
	v_lshlrev_b64 v[28:29], 13, v[12:13]
	v_or_b32_e32 v12, 6, v22
	v_lshlrev_b64 v[30:31], 13, v[12:13]
	v_or_b32_e32 v12, 8, v22
	v_lshlrev_b64 v[32:33], 13, v[12:13]
	v_or_b32_e32 v12, 10, v22
	v_mov_b32_e32 v23, v13
	v_lshlrev_b64 v[34:35], 13, v[12:13]
	v_or_b32_e32 v12, 12, v22
	v_lshlrev_b64 v[24:25], 13, v[22:23]
	v_lshlrev_b64 v[36:37], 13, v[12:13]
	v_or_b32_e32 v12, 14, v22
	v_lshl_add_u64 v[24:25], v[18:19], 0, v[24:25]
	v_lshlrev_b64 v[38:39], 13, v[12:13]
	v_or_b32_e32 v12, 16, v22
	v_lshl_add_u64 v[26:27], v[18:19], 0, v[26:27]
	v_lshl_add_u64 v[28:29], v[18:19], 0, v[28:29]
	v_lshl_add_u64 v[30:31], v[18:19], 0, v[30:31]
	v_lshl_add_u64 v[32:33], v[18:19], 0, v[32:33]
	v_lshl_add_u64 v[34:35], v[18:19], 0, v[34:35]
	v_lshl_add_u64 v[36:37], v[18:19], 0, v[36:37]
	v_lshl_add_u64 v[38:39], v[18:19], 0, v[38:39]
	global_load_dword v17, v[24:25], off nt
	global_load_dword v41, v[26:27], off nt
	global_load_dword v42, v[28:29], off nt
	global_load_dword v43, v[30:31], off nt
	global_load_dword v44, v[32:33], off nt
	global_load_dword v45, v[34:35], off nt
	global_load_dword v46, v[36:37], off nt
	global_load_dword v47, v[38:39], off nt
	v_lshlrev_b64 v[24:25], 13, v[12:13]
	v_or_b32_e32 v12, 18, v22
	v_lshlrev_b64 v[26:27], 13, v[12:13]
	v_or_b32_e32 v12, 20, v22
	v_lshlrev_b64 v[28:29], 13, v[12:13]
	v_or_b32_e32 v12, 22, v22
	v_lshlrev_b64 v[30:31], 13, v[12:13]
	v_or_b32_e32 v12, 24, v22
	v_lshlrev_b64 v[32:33], 13, v[12:13]
	v_or_b32_e32 v12, 26, v22
	v_lshlrev_b64 v[34:35], 13, v[12:13]
	v_or_b32_e32 v12, 28, v22
	v_lshlrev_b64 v[36:37], 13, v[12:13]
	v_or_b32_e32 v12, 30, v22
	v_lshl_add_u64 v[24:25], v[18:19], 0, v[24:25]
	v_lshlrev_b64 v[38:39], 13, v[12:13]
	v_or_b32_e32 v12, 32, v22
	v_lshl_add_u64 v[26:27], v[18:19], 0, v[26:27]
	v_lshl_add_u64 v[28:29], v[18:19], 0, v[28:29]
	v_lshl_add_u64 v[30:31], v[18:19], 0, v[30:31]
	v_lshl_add_u64 v[32:33], v[18:19], 0, v[32:33]
	v_lshl_add_u64 v[34:35], v[18:19], 0, v[34:35]
	v_lshl_add_u64 v[36:37], v[18:19], 0, v[36:37]
	v_lshl_add_u64 v[38:39], v[18:19], 0, v[38:39]
	global_load_dword v48, v[24:25], off nt
	global_load_dword v49, v[26:27], off nt
	global_load_dword v50, v[28:29], off nt
	global_load_dword v51, v[30:31], off nt
	global_load_dword v52, v[32:33], off nt
	global_load_dword v53, v[34:35], off nt
	global_load_dword v54, v[36:37], off nt
	global_load_dword v55, v[38:39], off nt
	v_lshlrev_b64 v[24:25], 13, v[12:13]
	v_or_b32_e32 v12, 34, v22
	v_lshlrev_b64 v[26:27], 13, v[12:13]
	v_or_b32_e32 v12, 36, v22
	v_lshlrev_b64 v[28:29], 13, v[12:13]
	v_or_b32_e32 v12, 38, v22
	v_lshlrev_b64 v[30:31], 13, v[12:13]
	v_or_b32_e32 v12, 40, v22
	v_lshlrev_b64 v[32:33], 13, v[12:13]
	v_or_b32_e32 v12, 42, v22
	v_lshlrev_b64 v[34:35], 13, v[12:13]
	v_or_b32_e32 v12, 44, v22
	v_lshlrev_b64 v[36:37], 13, v[12:13]
	v_or_b32_e32 v12, 46, v22
	v_lshlrev_b64 v[38:39], 13, v[12:13]
	v_lshl_add_u64 v[24:25], v[18:19], 0, v[24:25]
	v_lshl_add_u64 v[38:39], v[18:19], 0, v[38:39]
	v_or_b32_e32 v12, 48, v22
	v_lshl_add_u64 v[26:27], v[18:19], 0, v[26:27]
	v_lshl_add_u64 v[28:29], v[18:19], 0, v[28:29]
	v_lshl_add_u64 v[30:31], v[18:19], 0, v[30:31]
	v_lshl_add_u64 v[32:33], v[18:19], 0, v[32:33]
	v_lshl_add_u64 v[34:35], v[18:19], 0, v[34:35]
	v_lshl_add_u64 v[36:37], v[18:19], 0, v[36:37]
	global_load_dword v69, v[24:25], off nt
	global_load_dword v70, v[26:27], off nt
	global_load_dword v71, v[28:29], off nt
	global_load_dword v72, v[30:31], off nt
	global_load_dword v73, v[32:33], off nt
	global_load_dword v74, v[34:35], off nt
	global_load_dword v75, v[36:37], off nt
	s_nop 0
	global_load_dword v38, v[38:39], off nt
	v_lshlrev_b64 v[24:25], 13, v[12:13]
	v_or_b32_e32 v12, 50, v22
	v_lshlrev_b64 v[26:27], 13, v[12:13]
	v_or_b32_e32 v12, 52, v22
	v_lshlrev_b64 v[28:29], 13, v[12:13]
	v_or_b32_e32 v12, 54, v22
	v_lshlrev_b64 v[30:31], 13, v[12:13]
	v_or_b32_e32 v12, 56, v22
	v_lshlrev_b64 v[32:33], 13, v[12:13]
	v_or_b32_e32 v12, 58, v22
	v_lshlrev_b64 v[34:35], 13, v[12:13]
	v_or_b32_e32 v12, 60, v22
	v_lshlrev_b64 v[36:37], 13, v[12:13]
	v_or_b32_e32 v12, 62, v22
	v_lshl_add_u64 v[24:25], v[18:19], 0, v[24:25]
	v_lshl_add_u64 v[26:27], v[18:19], 0, v[26:27]
	v_lshl_add_u64 v[28:29], v[18:19], 0, v[28:29]
	v_lshlrev_b64 v[22:23], 13, v[12:13]
	v_lshl_add_u64 v[30:31], v[18:19], 0, v[30:31]
	v_lshl_add_u64 v[32:33], v[18:19], 0, v[32:33]
	v_lshl_add_u64 v[34:35], v[18:19], 0, v[34:35]
	v_lshl_add_u64 v[36:37], v[18:19], 0, v[36:37]
	v_lshl_add_u64 v[18:19], v[18:19], 0, v[22:23]
	global_load_dword v12, v[24:25], off nt
	global_load_dword v22, v[26:27], off nt
	global_load_dword v23, v[28:29], off nt
	s_nop 0
	global_load_dword v24, v[30:31], off nt
	global_load_dword v25, v[32:33], off nt
	global_load_dword v26, v[34:35], off nt
	global_load_dword v27, v[36:37], off nt
	global_load_dword v28, v[18:19], off nt
	s_waitcnt vmcnt(30)
; #define LAS __attribute__((address_space(3)))
; __device__ __forceinline__ unsigned pk2(float lo, float hi) { return pg8::cvt_pk_bf16(lo, hi); }
; __device__ __forceinline__ void transpose_item(const float* W, int ldw, const float* kgain, float scale, bf16_t* WT, int ldt, int k0, int n_src0, int n_dst0, LAS float* scr, int lane) {
;     ...
; #pragma unroll
;     for (int i = 0; i < 32; ++i) scr[(2 * i + (lane >> 5)) * 33 + (lane & 31)] = wv[i];
;     asm volatile("s_waitcnt lgkmcnt(0)" ::: "memory");
;     const int c = lane & 7;
; #pragma unroll
;     for (int j = 0; j < 4; ++j) { const int n = (lane >> 3) + 8 * j; const LAS float* s = scr + (8 * c) * 33 + n;
;         u32x4 o; o.x = pk2(s[0 * 33], s[1 * 33]); o.y = pk2(s[2 * 33], s[3 * 33]); o.z = pk2(s[4 * 33], s[5 * 33]); o.w = pk2(s[6 * 33], s[7 * 33]);
;         *(u32x4*)(WT + (size_t)(n_dst0 + n) * ldt + k0 + 8 * c) = o; }
;     asm volatile("s_waitcnt lgkmcnt(0)" ::: "memory");
; }
	ds_write2_b32 v5, v17, v41 offset1:66
	s_waitcnt vmcnt(28)
	ds_write2_b32 v5, v42, v43 offset0:132 offset1:198
	v_add_u32_e32 v17, 0x400, v5
	s_waitcnt vmcnt(26)
	ds_write2_b32 v17, v44, v45 offset0:8 offset1:74
	s_waitcnt vmcnt(24)
	ds_write2_b32 v17, v46, v47 offset0:140 offset1:206
	v_add_u32_e32 v17, 0x800, v5
	s_waitcnt vmcnt(22)
	ds_write2_b32 v17, v48, v49 offset0:16 offset1:82
	s_waitcnt vmcnt(20)
	ds_write2_b32 v17, v50, v51 offset0:148 offset1:214
	v_add_u32_e32 v17, 0xc00, v5
	s_waitcnt vmcnt(18)
	ds_write2_b32 v17, v52, v53 offset0:24 offset1:90
	s_waitcnt vmcnt(16)
	ds_write2_b32 v17, v54, v55 offset0:156 offset1:222
	v_add_u32_e32 v17, 0x1000, v5
	s_waitcnt vmcnt(14)
	ds_write2_b32 v17, v69, v70 offset0:32 offset1:98
	s_waitcnt vmcnt(12)
	ds_write2_b32 v17, v71, v72 offset0:164 offset1:230
	v_add_u32_e32 v17, 0x1400, v5
	s_waitcnt vmcnt(10)
	ds_write2_b32 v17, v73, v74 offset0:40 offset1:106
	s_waitcnt vmcnt(8)
	ds_write2_b32 v17, v75, v38 offset0:172 offset1:238
	v_add_u32_e32 v17, 0x1800, v5
	s_waitcnt vmcnt(6)
	ds_write2_b32 v17, v12, v22 offset0:48 offset1:114
	s_waitcnt vmcnt(4)
	ds_write2_b32 v17, v23, v24 offset0:180 offset1:246
	v_add_u32_e32 v12, 0x1c00, v5
	s_waitcnt vmcnt(2)
	ds_write2_b32 v12, v25, v26 offset0:56 offset1:122
	s_waitcnt vmcnt(0)
	ds_write2_b32 v12, v27, v28 offset0:188 offset1:254
	s_waitcnt lgkmcnt(0)
	v_lshlrev_b64 v[18:19], 25, v[20:21]
	ds_read2_b32 v[20:21], v11 offset0:33 offset1:41
	ds_read2_b32 v[22:23], v11 offset1:8
	ds_read2_b32 v[24:25], v11 offset0:66 offset1:74
	ds_read2_b32 v[26:27], v11 offset0:99 offset1:107
	ds_read2_b32 v[28:29], v11 offset0:132 offset1:140
	ds_read2_b32 v[30:31], v11 offset0:165 offset1:173
	ds_read2_b32 v[32:33], v11 offset0:198 offset1:206
	ds_read2_b32 v[34:35], v11 offset0:231 offset1:239
	v_lshl_add_u64 v[18:19], s[60:61], 0, v[18:19]
	v_mov_b32_e32 v17, v13
	v_lshl_add_u64 v[16:17], v[16:17], 1, v[18:19]
	v_lshlrev_b32_e32 v12, 1, v14
	v_lshl_add_u64 v[36:37], v[16:17], 0, v[12:13]
	v_or_b32_e32 v12, v40, v7
	v_lshlrev_b32_e32 v12, 14, v12
	s_waitcnt lgkmcnt(6)
	v_cvt_pk_bf16_f32 v16, v22, v20
	s_waitcnt lgkmcnt(4)
	v_cvt_pk_bf16_f32 v17, v24, v26
	s_waitcnt lgkmcnt(2)
	v_cvt_pk_bf16_f32 v18, v28, v30
	s_waitcnt lgkmcnt(0)
	v_cvt_pk_bf16_f32 v19, v32, v34
	v_lshl_add_u64 v[38:39], v[36:37], 0, v[12:13]
	global_store_dwordx4 v[38:39], v[16:19], off
	v_or_b32_e32 v12, v40, v15
	v_lshlrev_b32_e32 v12, 14, v12
	v_cvt_pk_bf16_f32 v16, v23, v21
	v_cvt_pk_bf16_f32 v17, v25, v27
	v_cvt_pk_bf16_f32 v18, v29, v31
	v_cvt_pk_bf16_f32 v19, v33, v35
	ds_read2_b32 v[22:23], v11 offset0:49 offset1:57
	ds_read2_b32 v[24:25], v11 offset0:16 offset1:24
	ds_read2_b32 v[26:27], v11 offset0:82 offset1:90
	ds_read2_b32 v[28:29], v11 offset0:115 offset1:123
	ds_read2_b32 v[30:31], v11 offset0:148 offset1:156
	ds_read2_b32 v[32:33], v11 offset0:181 offset1:189
	ds_read2_b32 v[34:35], v11 offset0:214 offset1:222
	ds_read2_b32 v[38:39], v11 offset0:247 offset1:255
	v_lshl_add_u64 v[20:21], v[36:37], 0, v[12:13]
	v_or_b32_e32 v12, v40, v56
	v_lshlrev_b32_e32 v12, 14, v12
	global_store_dwordx4 v[20:21], v[16:19], off
	v_lshl_add_u64 v[20:21], v[36:37], 0, v[12:13]
	v_or_b32_e32 v12, v40, v57
	s_waitcnt lgkmcnt(6)
	v_cvt_pk_bf16_f32 v16, v24, v22
	s_waitcnt lgkmcnt(4)
	v_cvt_pk_bf16_f32 v17, v26, v28
	s_waitcnt lgkmcnt(2)
	v_cvt_pk_bf16_f32 v18, v30, v32
	s_waitcnt lgkmcnt(0)
	v_cvt_pk_bf16_f32 v19, v34, v38
	v_lshlrev_b32_e32 v12, 14, v12
	global_store_dwordx4 v[20:21], v[16:19], off
	v_lshl_add_u64 v[20:21], v[36:37], 0, v[12:13]
	s_nop 0
	v_cvt_pk_bf16_f32 v16, v25, v23
	v_cvt_pk_bf16_f32 v17, v27, v29
	v_cvt_pk_bf16_f32 v18, v31, v33
	v_cvt_pk_bf16_f32 v19, v35, v39
	global_store_dwordx4 v[20:21], v[16:19], off
	s_waitcnt lgkmcnt(0)

; __device__ __forceinline__ void transpose_item(const float* W, int ldw, const float* kgain, float scale, bf16_t* WT, int ldt, int k0, int n_src0, int n_dst0, LAS float* scr, int lane) {
;     float wv[32];
; #pragma unroll
;     for (int i = 0; i < 32; ++i) wv[i] = W[(size_t)(k0 + 2 * i + (lane >> 5)) * ldw + n_src0 + (lane & 31)];
;     if (kgain) {
; #pragma unroll
;         for (int i = 0; i < 32; ++i) wv[i] *= kgain[k0 + 2 * i + (lane >> 5)] * scale; }
; __device__ __forceinline__ void phase_prologue(const P& p, unsigned char* ws, LAS unsigned char* lds, int wg, int nwg) {
;     ...
;         if (r < I_F1) { transpose_item(p.w_ff1 + (size_t)l * D * DFF, DFF, p.n_pre_ffn + l * D, 1.f, (bf16_t*)(ws + WS_WFF1) + (size_t)l * DFF * D, D, (r / (DFF / 32)) * 64, (r % (DFF / 32)) * 32, (r % (DFF / 32)) * 32, scr, lane); continue; } r -= I_F1;
.LBB0_26:
	s_andn2_saveexec_b64 s[44:45], s[88:89]
	s_cbranch_execz .LBB0_30
	v_add_u32_e32 v18, 0xffffc200, v12
	v_lshlrev_b32_e32 v12, 5, v12
	v_lshlrev_b64 v[16:17], 26, v[20:21]
	v_lshrrev_b32_e32 v18, 2, v18
	v_and_b32_e32 v50, 0x1fe0, v12
	v_lshl_add_u64 v[16:17], s[42:43], 0, v[16:17]
	v_and_b32_e32 v51, 0x3fffffc0, v18
	v_lshlrev_b32_e32 v12, 2, v50
	v_or_b32_e32 v69, v51, v8
	v_lshl_add_u64 v[16:17], v[16:17], 0, v[12:13]
	v_lshlrev_b32_e32 v12, 2, v10
	v_lshl_add_u64 v[42:43], v[16:17], 0, v[12:13]
	v_mov_b32_e32 v12, v69
	v_or_b32_e32 v18, 2, v69
	v_mov_b32_e32 v19, v13
	v_or_b32_e32 v22, 4, v69
	v_mov_b32_e32 v23, v13
	v_or_b32_e32 v24, 6, v69
	v_mov_b32_e32 v25, v13
	v_or_b32_e32 v26, 8, v69
	v_mov_b32_e32 v27, v13
	v_or_b32_e32 v28, 10, v69
	v_mov_b32_e32 v29, v13
	v_or_b32_e32 v30, 12, v69
	v_mov_b32_e32 v31, v13
	v_or_b32_e32 v32, 14, v69
	v_mov_b32_e32 v33, v13
	v_lshlrev_b64 v[16:17], 15, v[12:13]
	v_lshlrev_b64 v[18:19], 15, v[18:19]
	v_lshlrev_b64 v[22:23], 15, v[22:23]
	v_lshlrev_b64 v[24:25], 15, v[24:25]
	v_lshlrev_b64 v[26:27], 15, v[26:27]
	v_lshlrev_b64 v[28:29], 15, v[28:29]
	v_lshlrev_b64 v[30:31], 15, v[30:31]
	v_lshlrev_b64 v[32:33], 15, v[32:33]
	v_lshl_add_u64 v[16:17], v[42:43], 0, v[16:17]
	v_lshl_add_u64 v[18:19], v[42:43], 0, v[18:19]
	v_lshl_add_u64 v[22:23], v[42:43], 0, v[22:23]
	v_lshl_add_u64 v[24:25], v[42:43], 0, v[24:25]
	v_lshl_add_u64 v[26:27], v[42:43], 0, v[26:27]
	v_lshl_add_u64 v[28:29], v[42:43], 0, v[28:29]
	v_lshl_add_u64 v[30:31], v[42:43], 0, v[30:31]
	v_lshl_add_u64 v[32:33], v[42:43], 0, v[32:33]
	global_load_dword v16, v[16:17], off nt
	s_nop 0
	global_load_dword v17, v[18:19], off nt
	s_nop 0
	global_load_dword v22, v[22:23], off nt
	s_nop 0
	global_load_dword v23, v[24:25], off nt
	global_load_dword v18, v[26:27], off nt
	global_load_dword v19, v[28:29], off nt
	s_nop 0
	global_load_dword v24, v[30:31], off nt
	global_load_dword v25, v[32:33], off nt
	v_or_b32_e32 v26, 16, v69
	v_mov_b32_e32 v27, v13
	v_or_b32_e32 v28, 18, v69
	v_mov_b32_e32 v29, v13
	v_or_b32_e32 v30, 20, v69
	v_mov_b32_e32 v31, v13
	v_or_b32_e32 v32, 22, v69
	v_mov_b32_e32 v33, v13
	v_or_b32_e32 v34, 24, v69
	v_mov_b32_e32 v35, v13
	v_or_b32_e32 v36, 26, v69
	v_mov_b32_e32 v37, v13
	v_or_b32_e32 v38, 28, v69
	v_mov_b32_e32 v39, v13
	v_or_b32_e32 v40, 30, v69
	v_mov_b32_e32 v41, v13
	v_lshlrev_b64 v[26:27], 15, v[26:27]
	v_lshlrev_b64 v[28:29], 15, v[28:29]
	v_lshlrev_b64 v[30:31], 15, v[30:31]
	v_lshlrev_b64 v[32:33], 15, v[32:33]
	v_lshlrev_b64 v[34:35], 15, v[34:35]
	v_lshlrev_b64 v[36:37], 15, v[36:37]
	v_lshlrev_b64 v[38:39], 15, v[38:39]
	v_lshlrev_b64 v[40:41], 15, v[40:41]
	v_lshl_add_u64 v[26:27], v[42:43], 0, v[26:27]
	v_lshl_add_u64 v[28:29], v[42:43], 0, v[28:29]
	v_lshl_add_u64 v[30:31], v[42:43], 0, v[30:31]
	v_lshl_add_u64 v[32:33], v[42:43], 0, v[32:33]
	v_lshl_add_u64 v[34:35], v[42:43], 0, v[34:35]
	v_lshl_add_u64 v[36:37], v[42:43], 0, v[36:37]
	v_lshl_add_u64 v[38:39], v[42:43], 0, v[38:39]
	v_lshl_add_u64 v[40:41], v[42:43], 0, v[40:41]
	global_load_dword v26, v[26:27], off nt
	s_nop 0
	global_load_dword v27, v[28:29], off nt
	s_nop 0
	global_load_dword v30, v[30:31], off nt
	s_nop 0
	global_load_dword v31, v[32:33], off nt
	global_load_dword v28, v[34:35], off nt
	global_load_dword v29, v[36:37], off nt
	s_nop 0
	global_load_dword v32, v[38:39], off nt
	global_load_dword v33, v[40:41], off nt
	v_or_b32_e32 v34, 32, v69
	v_mov_b32_e32 v35, v13
	v_or_b32_e32 v36, 34, v69
	v_mov_b32_e32 v37, v13
	v_or_b32_e32 v38, 36, v69
	v_mov_b32_e32 v39, v13
	v_or_b32_e32 v40, 38, v69
	v_mov_b32_e32 v41, v13
	v_or_b32_e32 v44, 40, v69
	v_mov_b32_e32 v45, v13
	v_or_b32_e32 v46, 42, v69
	v_mov_b32_e32 v47, v13
	v_or_b32_e32 v48, 44, v69
	v_mov_b32_e32 v49, v13
	v_lshlrev_b64 v[34:35], 15, v[34:35]
	v_lshlrev_b64 v[36:37], 15, v[36:37]
	v_lshlrev_b64 v[38:39], 15, v[38:39]
	v_lshlrev_b64 v[40:41], 15, v[40:41]
	v_lshlrev_b64 v[44:45], 15, v[44:45]
	v_lshlrev_b64 v[46:47], 15, v[46:47]
	v_lshlrev_b64 v[48:49], 15, v[48:49]
	v_or_b32_e32 v52, 46, v69
	v_mov_b32_e32 v53, v13
	v_lshl_add_u64 v[34:35], v[42:43], 0, v[34:35]
	v_lshl_add_u64 v[36:37], v[42:43], 0, v[36:37]
	v_lshl_add_u64 v[38:39], v[42:43], 0, v[38:39]
	v_lshl_add_u64 v[40:41], v[42:43], 0, v[40:41]
	v_lshl_add_u64 v[44:45], v[42:43], 0, v[44:45]
	v_lshl_add_u64 v[46:47], v[42:43], 0, v[46:47]
	v_lshl_add_u64 v[48:49], v[42:43], 0, v[48:49]
	v_lshlrev_b64 v[52:53], 15, v[52:53]
	v_lshl_add_u64 v[52:53], v[42:43], 0, v[52:53]
	global_load_dword v34, v[34:35], off nt
	s_nop 0
	global_load_dword v35, v[36:37], off nt
	s_nop 0
	global_load_dword v38, v[38:39], off nt
	s_nop 0
	global_load_dword v39, v[40:41], off nt
	global_load_dword v36, v[44:45], off nt
	global_load_dword v37, v[46:47], off nt
	s_nop 0
	global_load_dword v40, v[48:49], off nt
	global_load_dword v41, v[52:53], off nt
	v_or_b32_e32 v44, 48, v69
	v_mov_b32_e32 v45, v13
	v_or_b32_e32 v46, 50, v69
	v_mov_b32_e32 v47, v13
	v_or_b32_e32 v48, 52, v69
	v_mov_b32_e32 v49, v13
	v_lshlrev_b64 v[44:45], 15, v[44:45]
	v_lshlrev_b64 v[46:47], 15, v[46:47]
	v_lshlrev_b64 v[48:49], 15, v[48:49]
	v_or_b32_e32 v52, 54, v69
	v_mov_b32_e32 v53, v13
	v_or_b32_e32 v54, 56, v69
	v_mov_b32_e32 v55, v13
	v_or_b32_e32 v70, 58, v69
	v_mov_b32_e32 v71, v13
	v_or_b32_e32 v72, 60, v69
	v_mov_b32_e32 v73, v13
	v_or_b32_e32 v74, 62, v69
	v_mov_b32_e32 v75, v13
	v_lshl_add_u64 v[44:45], v[42:43], 0, v[44:45]
	v_lshl_add_u64 v[46:47], v[42:43], 0, v[46:47]
	v_lshl_add_u64 v[48:49], v[42:43], 0, v[48:49]
	v_lshlrev_b64 v[52:53], 15, v[52:53]
	v_lshlrev_b64 v[54:55], 15, v[54:55]
	v_lshlrev_b64 v[70:71], 15, v[70:71]
	v_lshlrev_b64 v[72:73], 15, v[72:73]
	v_lshlrev_b64 v[74:75], 15, v[74:75]
	v_lshl_add_u64 v[52:53], v[42:43], 0, v[52:53]
	v_lshl_add_u64 v[54:55], v[42:43], 0, v[54:55]
	v_lshl_add_u64 v[70:71], v[42:43], 0, v[70:71]
	v_lshl_add_u64 v[72:73], v[42:43], 0, v[72:73]
	v_lshl_add_u64 v[74:75], v[42:43], 0, v[74:75]
	global_load_dword v42, v[44:45], off nt
	global_load_dword v43, v[46:47], off nt
	s_nop 0
	global_load_dword v48, v[48:49], off nt
	s_nop 0
	global_load_dword v49, v[52:53], off nt
	global_load_dword v46, v[54:55], off nt
	global_load_dword v47, v[70:71], off nt
	global_load_dword v44, v[72:73], off nt
	global_load_dword v45, v[74:75], off nt
	s_andn2_b64 vcc, exec, s[74:75]
	s_cbranch_vccnz .LBB0_29
; __device__ __forceinline__ void transpose_item(const float* W, int ldw, const float* kgain, float scale, bf16_t* WT, int ldt, int k0, int n_src0, int n_dst0, LAS float* scr, int lane) {
;     ...
;     if (kgain) {
; #pragma unroll
;         for (int i = 0; i < 32; ++i) wv[i] *= kgain[k0 + 2 * i + (lane >> 5)] * scale; }
	v_lshlrev_b32_e32 v52, 11, v20
	v_ashrrev_i32_e32 v53, 31, v52
	v_lshl_add_u64 v[52:53], v[52:53], 2, s[4:5]
	v_lshlrev_b32_e32 v12, 2, v12
	v_lshl_add_u64 v[52:53], v[52:53], 0, v[12:13]
	global_load_dword v54, v[52:53], off nt
	global_load_dword v55, v[52:53], off offset:8
	global_load_dword v70, v[52:53], off offset:16
	global_load_dword v71, v[52:53], off offset:24
	global_load_dword v72, v[52:53], off offset:32
	global_load_dword v73, v[52:53], off offset:40
	global_load_dword v74, v[52:53], off offset:48
	global_load_dword v75, v[52:53], off offset:56
	global_load_dword v76, v[52:53], off offset:64
	global_load_dword v77, v[52:53], off offset:72
	global_load_dword v78, v[52:53], off offset:80
	global_load_dword v79, v[52:53], off offset:88
	global_load_dword v80, v[52:53], off offset:96
	global_load_dword v81, v[52:53], off offset:104
	global_load_dword v82, v[52:53], off offset:112
	global_load_dword v83, v[52:53], off offset:120
	global_load_dword v84, v[52:53], off offset:128
	global_load_dword v85, v[52:53], off offset:136
	global_load_dword v86, v[52:53], off offset:144
	global_load_dword v87, v[52:53], off offset:152
	global_load_dword v88, v[52:53], off offset:160
	global_load_dword v89, v[52:53], off offset:168
	global_load_dword v90, v[52:53], off offset:176
	global_load_dword v91, v[52:53], off offset:184
	global_load_dword v92, v[52:53], off offset:192
	global_load_dword v93, v[52:53], off offset:200
	global_load_dword v94, v[52:53], off offset:208
	global_load_dword v95, v[52:53], off offset:216
	global_load_dword v96, v[52:53], off offset:224
	global_load_dword v97, v[52:53], off offset:232
	global_load_dword v98, v[52:53], off offset:240
	global_load_dword v99, v[52:53], off offset:248
	s_waitcnt vmcnt(30)
	v_pk_mul_f32 v[16:17], v[16:17], v[54:55]
	s_waitcnt vmcnt(28)
	v_pk_mul_f32 v[22:23], v[22:23], v[70:71]
	s_waitcnt vmcnt(26)
	v_pk_mul_f32 v[18:19], v[18:19], v[72:73]
	s_waitcnt vmcnt(24)
	v_pk_mul_f32 v[24:25], v[24:25], v[74:75]
	s_waitcnt vmcnt(22)
	v_pk_mul_f32 v[26:27], v[26:27], v[76:77]
	s_waitcnt vmcnt(20)
	v_pk_mul_f32 v[30:31], v[30:31], v[78:79]
	s_waitcnt vmcnt(18)
	v_pk_mul_f32 v[28:29], v[28:29], v[80:81]
	s_waitcnt vmcnt(16)
	v_pk_mul_f32 v[32:33], v[32:33], v[82:83]
	s_waitcnt vmcnt(14)
	v_pk_mul_f32 v[34:35], v[34:35], v[84:85]
	s_waitcnt vmcnt(12)
	v_pk_mul_f32 v[38:39], v[38:39], v[86:87]
	s_waitcnt vmcnt(10)
	v_pk_mul_f32 v[36:37], v[36:37], v[88:89]
	s_waitcnt vmcnt(8)
	v_pk_mul_f32 v[40:41], v[40:41], v[90:91]
	s_waitcnt vmcnt(6)
	v_pk_mul_f32 v[42:43], v[42:43], v[92:93]
	s_waitcnt vmcnt(4)
	v_pk_mul_f32 v[48:49], v[48:49], v[94:95]
	s_waitcnt vmcnt(2)
	v_pk_mul_f32 v[46:47], v[46:47], v[96:97]
	s_waitcnt vmcnt(0)
	v_pk_mul_f32 v[44:45], v[44:45], v[98:99]

; __device__ __forceinline__ void transpose_item(const float* W, int ldw, const float* kgain, float scale, bf16_t* WT, int ldt, int k0, int n_src0, int n_dst0, LAS float* scr, int lane) {
;     float wv[32];
; #pragma unroll
;     for (int i = 0; i < 32; ++i) wv[i] = W[(size_t)(k0 + 2 * i + (lane >> 5)) * ldw + n_src0 + (lane & 31)];
; __device__ __forceinline__ void phase_prologue(const P& p, unsigned char* ws, LAS unsigned char* lds, int wg, int nwg) {
;     ...
;         if (r < I_OUT) { transpose_item(p.w_out + (size_t)l * D * D, D, nullptr, 1.f, (bf16_t*)(ws + WS_WOUT) + (size_t)l * D * D, D, (r / (D / 32)) * 64, (r % (D / 32)) * 32, (r % (D / 32)) * 32, scr, lane); continue; } r -= I_OUT;
.LBB0_31:
	s_andn2_saveexec_b64 s[44:45], s[86:87]
	s_cbranch_execz .LBB0_33
	v_ashrrev_i32_e32 v21, 31, v20
	v_lshlrev_b64 v[16:17], 24, v[20:21]
	v_lshl_add_u64 v[18:19], s[40:41], 0, v[16:17]
	v_and_b32_e32 v16, 0x3fc0, v12
	v_lshlrev_b32_e32 v12, 5, v12
	v_and_b32_e32 v40, 0x7e0, v12
	v_add_u32_e32 v16, 0xffffca00, v16
	v_lshlrev_b32_e32 v12, 2, v40
	v_or_b32_e32 v22, v16, v8
	v_lshl_add_u64 v[18:19], v[18:19], 0, v[12:13]
	v_lshlrev_b32_e32 v12, 2, v10
	v_lshl_add_u64 v[18:19], v[18:19], 0, v[12:13]
	v_or_b32_e32 v12, 2, v22
	v_lshlrev_b64 v[26:27], 13, v[12:13]
	v_or_b32_e32 v12, 4, v22
	v_lshlrev_b64 v[28:29], 13, v[12:13]
	v_or_b32_e32 v12, 6, v22
	v_lshlrev_b64 v[30:31], 13, v[12:13]
	v_or_b32_e32 v12, 8, v22
	v_lshlrev_b64 v[32:33], 13, v[12:13]
	v_or_b32_e32 v12, 10, v22
	v_mov_b32_e32 v23, v13
	v_lshlrev_b64 v[34:35], 13, v[12:13]
	v_or_b32_e32 v12, 12, v22
	v_lshlrev_b64 v[24:25], 13, v[22:23]
	v_lshlrev_b64 v[36:37], 13, v[12:13]
	v_or_b32_e32 v12, 14, v22
	v_lshl_add_u64 v[24:25], v[18:19], 0, v[24:25]
	v_lshlrev_b64 v[38:39], 13, v[12:13]
	v_or_b32_e32 v12, 16, v22
	v_lshl_add_u64 v[26:27], v[18:19], 0, v[26:27]
	v_lshl_add_u64 v[28:29], v[18:19], 0, v[28:29]
	v_lshl_add_u64 v[30:31], v[18:19], 0, v[30:31]
	v_lshl_add_u64 v[32:33], v[18:19], 0, v[32:33]
	v_lshl_add_u64 v[34:35], v[18:19], 0, v[34:35]
	v_lshl_add_u64 v[36:37], v[18:19], 0, v[36:37]
	v_lshl_add_u64 v[38:39], v[18:19], 0, v[38:39]
	global_load_dword v17, v[24:25], off nt
	global_load_dword v41, v[26:27], off nt
	global_load_dword v42, v[28:29], off nt
	global_load_dword v43, v[30:31], off nt
	global_load_dword v44, v[32:33], off nt
	global_load_dword v45, v[34:35], off nt
	global_load_dword v46, v[36:37], off nt
	global_load_dword v47, v[38:39], off nt
	v_lshlrev_b64 v[24:25], 13, v[12:13]
	v_or_b32_e32 v12, 18, v22
	v_lshlrev_b64 v[26:27], 13, v[12:13]
	v_or_b32_e32 v12, 20, v22
	v_lshlrev_b64 v[28:29], 13, v[12:13]
	v_or_b32_e32 v12, 22, v22
	v_lshlrev_b64 v[30:31], 13, v[12:13]
	v_or_b32_e32 v12, 24, v22
	v_lshlrev_b64 v[32:33], 13, v[12:13]
	v_or_b32_e32 v12, 26, v22
	v_lshlrev_b64 v[34:35], 13, v[12:13]
	v_or_b32_e32 v12, 28, v22
	v_lshlrev_b64 v[36:37], 13, v[12:13]
	v_or_b32_e32 v12, 30, v22
	v_lshl_add_u64 v[24:25], v[18:19], 0, v[24:25]
	v_lshlrev_b64 v[38:39], 13, v[12:13]
	v_or_b32_e32 v12, 32, v22
	v_lshl_add_u64 v[26:27], v[18:19], 0, v[26:27]
	v_lshl_add_u64 v[28:29], v[18:19], 0, v[28:29]
	v_lshl_add_u64 v[30:31], v[18:19], 0, v[30:31]
	v_lshl_add_u64 v[32:33], v[18:19], 0, v[32:33]
	v_lshl_add_u64 v[34:35], v[18:19], 0, v[34:35]
	v_lshl_add_u64 v[36:37], v[18:19], 0, v[36:37]
	v_lshl_add_u64 v[38:39], v[18:19], 0, v[38:39]
	global_load_dword v48, v[24:25], off nt
	global_load_dword v49, v[26:27], off nt
	global_load_dword v50, v[28:29], off nt
	global_load_dword v51, v[30:31], off nt
	global_load_dword v52, v[32:33], off nt
	global_load_dword v53, v[34:35], off nt
	global_load_dword v54, v[36:37], off nt
	global_load_dword v55, v[38:39], off nt
	v_lshlrev_b64 v[24:25], 13, v[12:13]
	v_or_b32_e32 v12, 34, v22
	v_lshlrev_b64 v[26:27], 13, v[12:13]
	v_or_b32_e32 v12, 36, v22
	v_lshlrev_b64 v[28:29], 13, v[12:13]
	v_or_b32_e32 v12, 38, v22
	v_lshlrev_b64 v[30:31], 13, v[12:13]
	v_or_b32_e32 v12, 40, v22
	v_lshlrev_b64 v[32:33], 13, v[12:13]
	v_or_b32_e32 v12, 42, v22
	v_lshlrev_b64 v[34:35], 13, v[12:13]
	v_or_b32_e32 v12, 44, v22
	v_lshlrev_b64 v[36:37], 13, v[12:13]
	v_or_b32_e32 v12, 46, v22
	v_lshlrev_b64 v[38:39], 13, v[12:13]
	v_lshl_add_u64 v[24:25], v[18:19], 0, v[24:25]
	v_lshl_add_u64 v[38:39], v[18:19], 0, v[38:39]
	v_or_b32_e32 v12, 48, v22
	v_lshl_add_u64 v[26:27], v[18:19], 0, v[26:27]
	v_lshl_add_u64 v[28:29], v[18:19], 0, v[28:29]
	v_lshl_add_u64 v[30:31], v[18:19], 0, v[30:31]
	v_lshl_add_u64 v[32:33], v[18:19], 0, v[32:33]
	v_lshl_add_u64 v[34:35], v[18:19], 0, v[34:35]
	v_lshl_add_u64 v[36:37], v[18:19], 0, v[36:37]
	global_load_dword v69, v[24:25], off nt
	global_load_dword v70, v[26:27], off nt
	global_load_dword v71, v[28:29], off nt
	global_load_dword v72, v[30:31], off nt
	global_load_dword v73, v[32:33], off nt
	global_load_dword v74, v[34:35], off nt
	global_load_dword v75, v[36:37], off nt
	s_nop 0
	global_load_dword v38, v[38:39], off nt
	v_lshlrev_b64 v[24:25], 13, v[12:13]
	v_or_b32_e32 v12, 50, v22
	v_lshlrev_b64 v[26:27], 13, v[12:13]
	v_or_b32_e32 v12, 52, v22
	v_lshlrev_b64 v[28:29], 13, v[12:13]
	v_or_b32_e32 v12, 54, v22
	v_lshlrev_b64 v[30:31], 13, v[12:13]
	v_or_b32_e32 v12, 56, v22
	v_lshlrev_b64 v[32:33], 13, v[12:13]
	v_or_b32_e32 v12, 58, v22
	v_lshlrev_b64 v[34:35], 13, v[12:13]
	v_or_b32_e32 v12, 60, v22
	v_lshlrev_b64 v[36:37], 13, v[12:13]
	v_or_b32_e32 v12, 62, v22
	v_lshl_add_u64 v[24:25], v[18:19], 0, v[24:25]
	v_lshl_add_u64 v[26:27], v[18:19], 0, v[26:27]
	v_lshl_add_u64 v[28:29], v[18:19], 0, v[28:29]
	v_lshlrev_b64 v[22:23], 13, v[12:13]
	v_lshl_add_u64 v[30:31], v[18:19], 0, v[30:31]
	v_lshl_add_u64 v[32:33], v[18:19], 0, v[32:33]
	v_lshl_add_u64 v[34:35], v[18:19], 0, v[34:35]
	v_lshl_add_u64 v[36:37], v[18:19], 0, v[36:37]
	v_lshl_add_u64 v[18:19], v[18:19], 0, v[22:23]
	global_load_dword v12, v[24:25], off nt
	global_load_dword v22, v[26:27], off nt
	global_load_dword v23, v[28:29], off nt
	s_nop 0
	global_load_dword v24, v[30:31], off nt
	global_load_dword v25, v[32:33], off nt
	global_load_dword v26, v[34:35], off nt
	global_load_dword v27, v[36:37], off nt
	global_load_dword v28, v[18:19], off nt
	s_waitcnt vmcnt(30)
; #define LAS __attribute__((address_space(3)))
; __device__ __forceinline__ unsigned pk2(float lo, float hi) { return pg8::cvt_pk_bf16(lo, hi); }
; __device__ __forceinline__ void transpose_item(const float* W, int ldw, const float* kgain, float scale, bf16_t* WT, int ldt, int k0, int n_src0, int n_dst0, LAS float* scr, int lane) {
;     ...
; #pragma unroll
;     for (int i = 0; i < 32; ++i) scr[(2 * i + (lane >> 5)) * 33 + (lane & 31)] = wv[i];
;     asm volatile("s_waitcnt lgkmcnt(0)" ::: "memory");
;     const int c = lane & 7;
; #pragma unroll
;     for (int j = 0; j < 4; ++j) { const int n = (lane >> 3) + 8 * j; const LAS float* s = scr + (8 * c) * 33 + n;
;         u32x4 o; o.x = pk2(s[0 * 33], s[1 * 33]); o.y = pk2(s[2 * 33], s[3 * 33]); o.z = pk2(s[4 * 33], s[5 * 33]); o.w = pk2(s[6 * 33], s[7 * 33]);
;         *(u32x4*)(WT + (size_t)(n_dst0 + n) * ldt + k0 + 8 * c) = o; }
;     asm volatile("s_waitcnt lgkmcnt(0)" ::: "memory");
; }
	ds_write2_b32 v5, v17, v41 offset1:66
	s_waitcnt vmcnt(28)
	ds_write2_b32 v5, v42, v43 offset0:132 offset1:198
	v_add_u32_e32 v17, 0x400, v5
	s_waitcnt vmcnt(26)
	ds_write2_b32 v17, v44, v45 offset0:8 offset1:74
	s_waitcnt vmcnt(24)
	ds_write2_b32 v17, v46, v47 offset0:140 offset1:206
	v_add_u32_e32 v17, 0x800, v5
	s_waitcnt vmcnt(22)
	ds_write2_b32 v17, v48, v49 offset0:16 offset1:82
	s_waitcnt vmcnt(20)
	ds_write2_b32 v17, v50, v51 offset0:148 offset1:214
	v_add_u32_e32 v17, 0xc00, v5
	s_waitcnt vmcnt(18)
	ds_write2_b32 v17, v52, v53 offset0:24 offset1:90
	s_waitcnt vmcnt(16)
	ds_write2_b32 v17, v54, v55 offset0:156 offset1:222
	v_add_u32_e32 v17, 0x1000, v5
	s_waitcnt vmcnt(14)
	ds_write2_b32 v17, v69, v70 offset0:32 offset1:98
	s_waitcnt vmcnt(12)
	ds_write2_b32 v17, v71, v72 offset0:164 offset1:230
	v_add_u32_e32 v17, 0x1400, v5
	s_waitcnt vmcnt(10)
	ds_write2_b32 v17, v73, v74 offset0:40 offset1:106
	s_waitcnt vmcnt(8)
	ds_write2_b32 v17, v75, v38 offset0:172 offset1:238
	v_add_u32_e32 v17, 0x1800, v5
	s_waitcnt vmcnt(6)
	ds_write2_b32 v17, v12, v22 offset0:48 offset1:114
	s_waitcnt vmcnt(4)
	ds_write2_b32 v17, v23, v24 offset0:180 offset1:246
	v_add_u32_e32 v12, 0x1c00, v5
	s_waitcnt vmcnt(2)
	ds_write2_b32 v12, v25, v26 offset0:56 offset1:122
	s_waitcnt vmcnt(0)
	ds_write2_b32 v12, v27, v28 offset0:188 offset1:254
	s_waitcnt lgkmcnt(0)
	v_lshlrev_b64 v[18:19], 23, v[20:21]
	ds_read2_b32 v[20:21], v11 offset0:33 offset1:41
	ds_read2_b32 v[22:23], v11 offset1:8
	ds_read2_b32 v[24:25], v11 offset0:66 offset1:74
	ds_read2_b32 v[26:27], v11 offset0:99 offset1:107
	ds_read2_b32 v[28:29], v11 offset0:132 offset1:140
	ds_read2_b32 v[30:31], v11 offset0:165 offset1:173
	ds_read2_b32 v[32:33], v11 offset0:198 offset1:206
	ds_read2_b32 v[34:35], v11 offset0:231 offset1:239
	v_lshl_add_u64 v[18:19], s[64:65], 0, v[18:19]
	v_mov_b32_e32 v17, v13
	v_lshl_add_u64 v[16:17], v[16:17], 1, v[18:19]
	v_lshlrev_b32_e32 v12, 1, v14
	v_lshl_add_u64 v[36:37], v[16:17], 0, v[12:13]
	v_or_b32_e32 v12, v40, v7
	v_lshlrev_b32_e32 v12, 12, v12
	s_waitcnt lgkmcnt(6)
	v_cvt_pk_bf16_f32 v16, v22, v20
	s_waitcnt lgkmcnt(4)
	v_cvt_pk_bf16_f32 v17, v24, v26
	s_waitcnt lgkmcnt(2)
	v_cvt_pk_bf16_f32 v18, v28, v30
	s_waitcnt lgkmcnt(0)
	v_cvt_pk_bf16_f32 v19, v32, v34
	v_lshl_add_u64 v[38:39], v[36:37], 0, v[12:13]
	global_store_dwordx4 v[38:39], v[16:19], off
	v_or_b32_e32 v12, v40, v15
	v_lshlrev_b32_e32 v12, 12, v12
	v_cvt_pk_bf16_f32 v16, v23, v21
	v_cvt_pk_bf16_f32 v17, v25, v27
	v_cvt_pk_bf16_f32 v18, v29, v31
	v_cvt_pk_bf16_f32 v19, v33, v35
	ds_read2_b32 v[22:23], v11 offset0:49 offset1:57
	ds_read2_b32 v[24:25], v11 offset0:16 offset1:24
	ds_read2_b32 v[26:27], v11 offset0:82 offset1:90
	ds_read2_b32 v[28:29], v11 offset0:115 offset1:123
	ds_read2_b32 v[30:31], v11 offset0:148 offset1:156
	ds_read2_b32 v[32:33], v11 offset0:181 offset1:189
	ds_read2_b32 v[34:35], v11 offset0:214 offset1:222
	ds_read2_b32 v[38:39], v11 offset0:247 offset1:255
	v_lshl_add_u64 v[20:21], v[36:37], 0, v[12:13]
	v_or_b32_e32 v12, v40, v56
	v_lshlrev_b32_e32 v12, 12, v12
	global_store_dwordx4 v[20:21], v[16:19], off
	v_lshl_add_u64 v[20:21], v[36:37], 0, v[12:13]
	v_or_b32_e32 v12, v40, v57
	s_waitcnt lgkmcnt(6)
	v_cvt_pk_bf16_f32 v16, v24, v22
	s_waitcnt lgkmcnt(4)
	v_cvt_pk_bf16_f32 v17, v26, v28
	s_waitcnt lgkmcnt(2)
	v_cvt_pk_bf16_f32 v18, v30, v32
	s_waitcnt lgkmcnt(0)
	v_cvt_pk_bf16_f32 v19, v34, v38
	v_lshlrev_b32_e32 v12, 12, v12
	global_store_dwordx4 v[20:21], v[16:19], off
	v_lshl_add_u64 v[20:21], v[36:37], 0, v[12:13]
	s_nop 0
	v_cvt_pk_bf16_f32 v16, v25, v23
	v_cvt_pk_bf16_f32 v17, v27, v29
	v_cvt_pk_bf16_f32 v18, v31, v33
	v_cvt_pk_bf16_f32 v19, v35, v39
	global_store_dwordx4 v[20:21], v[16:19], off
	s_waitcnt lgkmcnt(0)

; __device__ __forceinline__ void transpose_item(const float* W, int ldw, const float* kgain, float scale, bf16_t* WT, int ldt, int k0, int n_src0, int n_dst0, LAS float* scr, int lane) {
;     float wv[32];
; #pragma unroll
;     for (int i = 0; i < 32; ++i) wv[i] = W[(size_t)(k0 + 2 * i + (lane >> 5)) * ldw + n_src0 + (lane & 31)];
; __device__ __forceinline__ void phase_prologue(const P& p, unsigned char* ws, LAS unsigned char* lds, int wg, int nwg) {
;     ...
;         if (r < I_UG) { transpose_item(p.w_gup + (size_t)l * GVW * D, D, nullptr, 1.f, (bf16_t*)(ws + WS_WUG) + (size_t)l * D * GVW, GVW, (r / (D / 32)) * 64, (r % (D / 32)) * 32, (r % (D / 32)) * 32, scr, lane); continue; } r -= I_UG;
.LBB0_34:
	s_andn2_saveexec_b64 s[44:45], s[84:85]
	s_cbranch_execz .LBB0_36
	v_ashrrev_i32_e32 v21, 31, v20
	v_lshlrev_b64 v[16:17], 23, v[20:21]
	v_lshl_add_u64 v[18:19], s[38:39], 0, v[16:17]
	v_and_b32_e32 v16, 0x3fc0, v12
	v_lshlrev_b32_e32 v12, 5, v12
	v_and_b32_e32 v40, 0x7e0, v12
	v_add_u32_e32 v16, 0xffffce00, v16
	v_lshlrev_b32_e32 v12, 2, v40
	v_or_b32_e32 v22, v16, v8
	v_lshl_add_u64 v[18:19], v[18:19], 0, v[12:13]
	v_lshlrev_b32_e32 v12, 2, v10
	v_lshl_add_u64 v[18:19], v[18:19], 0, v[12:13]
	v_or_b32_e32 v12, 2, v22
	v_lshlrev_b64 v[26:27], 13, v[12:13]
	v_or_b32_e32 v12, 4, v22
	v_lshlrev_b64 v[28:29], 13, v[12:13]
	v_or_b32_e32 v12, 6, v22
	v_lshlrev_b64 v[30:31], 13, v[12:13]
	v_or_b32_e32 v12, 8, v22
	v_lshlrev_b64 v[32:33], 13, v[12:13]
	v_or_b32_e32 v12, 10, v22
	v_mov_b32_e32 v23, v13
	v_lshlrev_b64 v[34:35], 13, v[12:13]
	v_or_b32_e32 v12, 12, v22
	v_lshlrev_b64 v[24:25], 13, v[22:23]
	v_lshlrev_b64 v[36:37], 13, v[12:13]
	v_or_b32_e32 v12, 14, v22
	v_lshl_add_u64 v[24:25], v[18:19], 0, v[24:25]
	v_lshlrev_b64 v[38:39], 13, v[12:13]
	v_or_b32_e32 v12, 16, v22
	v_lshl_add_u64 v[26:27], v[18:19], 0, v[26:27]
	v_lshl_add_u64 v[28:29], v[18:19], 0, v[28:29]
	v_lshl_add_u64 v[30:31], v[18:19], 0, v[30:31]
	v_lshl_add_u64 v[32:33], v[18:19], 0, v[32:33]
	v_lshl_add_u64 v[34:35], v[18:19], 0, v[34:35]
	v_lshl_add_u64 v[36:37], v[18:19], 0, v[36:37]
	v_lshl_add_u64 v[38:39], v[18:19], 0, v[38:39]
	global_load_dword v17, v[24:25], off nt
	global_load_dword v41, v[26:27], off nt
	global_load_dword v42, v[28:29], off nt
	global_load_dword v43, v[30:31], off nt
	global_load_dword v44, v[32:33], off nt
	global_load_dword v45, v[34:35], off nt
	global_load_dword v46, v[36:37], off nt
	global_load_dword v47, v[38:39], off nt
	v_lshlrev_b64 v[24:25], 13, v[12:13]
	v_or_b32_e32 v12, 18, v22
	v_lshlrev_b64 v[26:27], 13, v[12:13]
	v_or_b32_e32 v12, 20, v22
	v_lshlrev_b64 v[28:29], 13, v[12:13]
	v_or_b32_e32 v12, 22, v22
	v_lshlrev_b64 v[30:31], 13, v[12:13]
	v_or_b32_e32 v12, 24, v22
	v_lshlrev_b64 v[32:33], 13, v[12:13]
	v_or_b32_e32 v12, 26, v22
	v_lshlrev_b64 v[34:35], 13, v[12:13]
	v_or_b32_e32 v12, 28, v22
	v_lshlrev_b64 v[36:37], 13, v[12:13]
	v_or_b32_e32 v12, 30, v22
	v_lshl_add_u64 v[24:25], v[18:19], 0, v[24:25]
	v_lshlrev_b64 v[38:39], 13, v[12:13]
	v_or_b32_e32 v12, 32, v22
	v_lshl_add_u64 v[26:27], v[18:19], 0, v[26:27]
	v_lshl_add_u64 v[28:29], v[18:19], 0, v[28:29]
	v_lshl_add_u64 v[30:31], v[18:19], 0, v[30:31]
	v_lshl_add_u64 v[32:33], v[18:19], 0, v[32:33]
	v_lshl_add_u64 v[34:35], v[18:19], 0, v[34:35]
	v_lshl_add_u64 v[36:37], v[18:19], 0, v[36:37]
	v_lshl_add_u64 v[38:39], v[18:19], 0, v[38:39]
	global_load_dword v48, v[24:25], off nt
	global_load_dword v49, v[26:27], off nt
	global_load_dword v50, v[28:29], off nt
	global_load_dword v51, v[30:31], off nt
	global_load_dword v52, v[32:33], off nt
	global_load_dword v53, v[34:35], off nt
	global_load_dword v54, v[36:37], off nt
	global_load_dword v55, v[38:39], off nt
	v_lshlrev_b64 v[24:25], 13, v[12:13]
	v_or_b32_e32 v12, 34, v22
	v_lshlrev_b64 v[26:27], 13, v[12:13]
	v_or_b32_e32 v12, 36, v22
	v_lshlrev_b64 v[28:29], 13, v[12:13]
	v_or_b32_e32 v12, 38, v22
	v_lshlrev_b64 v[30:31], 13, v[12:13]
	v_or_b32_e32 v12, 40, v22
	v_lshlrev_b64 v[32:33], 13, v[12:13]
	v_or_b32_e32 v12, 42, v22
	v_lshlrev_b64 v[34:35], 13, v[12:13]
	v_or_b32_e32 v12, 44, v22
	v_lshlrev_b64 v[36:37], 13, v[12:13]
	v_or_b32_e32 v12, 46, v22
	v_lshlrev_b64 v[38:39], 13, v[12:13]
	v_lshl_add_u64 v[24:25], v[18:19], 0, v[24:25]
	v_lshl_add_u64 v[38:39], v[18:19], 0, v[38:39]
	v_or_b32_e32 v12, 48, v22
	v_lshl_add_u64 v[26:27], v[18:19], 0, v[26:27]
	v_lshl_add_u64 v[28:29], v[18:19], 0, v[28:29]
	v_lshl_add_u64 v[30:31], v[18:19], 0, v[30:31]
	v_lshl_add_u64 v[32:33], v[18:19], 0, v[32:33]
	v_lshl_add_u64 v[34:35], v[18:19], 0, v[34:35]
	v_lshl_add_u64 v[36:37], v[18:19], 0, v[36:37]
	global_load_dword v69, v[24:25], off nt
	global_load_dword v70, v[26:27], off nt
	global_load_dword v71, v[28:29], off nt
	global_load_dword v72, v[30:31], off nt
	global_load_dword v73, v[32:33], off nt
	global_load_dword v74, v[34:35], off nt
	global_load_dword v75, v[36:37], off nt
	s_nop 0
	global_load_dword v38, v[38:39], off nt
	v_lshlrev_b64 v[24:25], 13, v[12:13]
	v_or_b32_e32 v12, 50, v22
	v_lshlrev_b64 v[26:27], 13, v[12:13]
	v_or_b32_e32 v12, 52, v22
	v_lshlrev_b64 v[28:29], 13, v[12:13]
	v_or_b32_e32 v12, 54, v22
	v_lshlrev_b64 v[30:31], 13, v[12:13]
	v_or_b32_e32 v12, 56, v22
	v_lshlrev_b64 v[32:33], 13, v[12:13]
	v_or_b32_e32 v12, 58, v22
	v_lshlrev_b64 v[34:35], 13, v[12:13]
	v_or_b32_e32 v12, 60, v22
	v_lshlrev_b64 v[36:37], 13, v[12:13]
	v_or_b32_e32 v12, 62, v22
	v_lshl_add_u64 v[24:25], v[18:19], 0, v[24:25]
	v_lshl_add_u64 v[26:27], v[18:19], 0, v[26:27]
	v_lshl_add_u64 v[28:29], v[18:19], 0, v[28:29]
	v_lshlrev_b64 v[22:23], 13, v[12:13]
	v_lshl_add_u64 v[30:31], v[18:19], 0, v[30:31]
	v_lshl_add_u64 v[32:33], v[18:19], 0, v[32:33]
	v_lshl_add_u64 v[34:35], v[18:19], 0, v[34:35]
	v_lshl_add_u64 v[36:37], v[18:19], 0, v[36:37]
	v_lshl_add_u64 v[18:19], v[18:19], 0, v[22:23]
	global_load_dword v12, v[24:25], off nt
	global_load_dword v22, v[26:27], off nt
	global_load_dword v23, v[28:29], off nt
	s_nop 0
	global_load_dword v24, v[30:31], off nt
	global_load_dword v25, v[32:33], off nt
	global_load_dword v26, v[34:35], off nt
	global_load_dword v27, v[36:37], off nt
	global_load_dword v28, v[18:19], off nt
	s_waitcnt vmcnt(30)
; #define LAS __attribute__((address_space(3)))
; __device__ __forceinline__ unsigned pk2(float lo, float hi) { return pg8::cvt_pk_bf16(lo, hi); }
; __device__ __forceinline__ void transpose_item(const float* W, int ldw, const float* kgain, float scale, bf16_t* WT, int ldt, int k0, int n_src0, int n_dst0, LAS float* scr, int lane) {
;     ...
;     for (int i = 0; i < 32; ++i) scr[(2 * i + (lane >> 5)) * 33 + (lane & 31)] = wv[i];
;     asm volatile("s_waitcnt lgkmcnt(0)" ::: "memory");
;     const int c = lane & 7;
; #pragma unroll
;     for (int j = 0; j < 4; ++j) { const int n = (lane >> 3) + 8 * j; const LAS float* s = scr + (8 * c) * 33 + n;
;         u32x4 o; o.x = pk2(s[0 * 33], s[1 * 33]); o.y = pk2(s[2 * 33], s[3 * 33]); o.z = pk2(s[4 * 33], s[5 * 33]); o.w = pk2(s[6 * 33], s[7 * 33]);
;         *(u32x4*)(WT + (size_t)(n_dst0 + n) * ldt + k0 + 8 * c) = o; }
;     asm volatile("s_waitcnt lgkmcnt(0)" ::: "memory");
	ds_write2_b32 v5, v17, v41 offset1:66
	s_waitcnt vmcnt(28)
	ds_write2_b32 v5, v42, v43 offset0:132 offset1:198
	v_add_u32_e32 v17, 0x400, v5
	s_waitcnt vmcnt(26)
	ds_write2_b32 v17, v44, v45 offset0:8 offset1:74
	s_waitcnt vmcnt(24)
	ds_write2_b32 v17, v46, v47 offset0:140 offset1:206
	v_add_u32_e32 v17, 0x800, v5
	s_waitcnt vmcnt(22)
	ds_write2_b32 v17, v48, v49 offset0:16 offset1:82
	s_waitcnt vmcnt(20)
	ds_write2_b32 v17, v50, v51 offset0:148 offset1:214
	v_add_u32_e32 v17, 0xc00, v5
	s_waitcnt vmcnt(18)
	ds_write2_b32 v17, v52, v53 offset0:24 offset1:90
	s_waitcnt vmcnt(16)
	ds_write2_b32 v17, v54, v55 offset0:156 offset1:222
	v_add_u32_e32 v17, 0x1000, v5
	s_waitcnt vmcnt(14)
	ds_write2_b32 v17, v69, v70 offset0:32 offset1:98
	s_waitcnt vmcnt(12)
	ds_write2_b32 v17, v71, v72 offset0:164 offset1:230
	v_add_u32_e32 v17, 0x1400, v5
	s_waitcnt vmcnt(10)
	ds_write2_b32 v17, v73, v74 offset0:40 offset1:106
	s_waitcnt vmcnt(8)
	ds_write2_b32 v17, v75, v38 offset0:172 offset1:238
	v_add_u32_e32 v17, 0x1800, v5
	s_waitcnt vmcnt(6)
	ds_write2_b32 v17, v12, v22 offset0:48 offset1:114
	s_waitcnt vmcnt(4)
	ds_write2_b32 v17, v23, v24 offset0:180 offset1:246
	v_add_u32_e32 v12, 0x1c00, v5
	s_waitcnt vmcnt(2)
	ds_write2_b32 v12, v25, v26 offset0:56 offset1:122
	s_waitcnt vmcnt(0)
	ds_write2_b32 v12, v27, v28 offset0:188 offset1:254
	s_waitcnt lgkmcnt(0)
	v_lshlrev_b64 v[18:19], 22, v[20:21]
	ds_read2_b32 v[20:21], v11 offset0:33 offset1:41
	ds_read2_b32 v[22:23], v11 offset1:8
	ds_read2_b32 v[24:25], v11 offset0:66 offset1:74
	ds_read2_b32 v[26:27], v11 offset0:99 offset1:107
	ds_read2_b32 v[28:29], v11 offset0:132 offset1:140
	ds_read2_b32 v[30:31], v11 offset0:165 offset1:173
	ds_read2_b32 v[32:33], v11 offset0:198 offset1:206
	ds_read2_b32 v[34:35], v11 offset0:231 offset1:239
	v_lshl_add_u64 v[18:19], s[66:67], 0, v[18:19]
	v_mov_b32_e32 v17, v13
	v_lshl_add_u64 v[16:17], v[16:17], 1, v[18:19]
	v_lshlrev_b32_e32 v12, 1, v14
	v_lshl_add_u64 v[36:37], v[16:17], 0, v[12:13]
	v_or_b32_e32 v12, v40, v7
	v_lshlrev_b32_e32 v12, 11, v12
	s_waitcnt lgkmcnt(6)
	v_cvt_pk_bf16_f32 v16, v22, v20
	s_waitcnt lgkmcnt(4)
	v_cvt_pk_bf16_f32 v17, v24, v26
	s_waitcnt lgkmcnt(2)
	v_cvt_pk_bf16_f32 v18, v28, v30
	s_waitcnt lgkmcnt(0)
	v_cvt_pk_bf16_f32 v19, v32, v34
	v_lshl_add_u64 v[38:39], v[36:37], 0, v[12:13]
	global_store_dwordx4 v[38:39], v[16:19], off
	v_or_b32_e32 v12, v40, v15
	v_lshlrev_b32_e32 v12, 11, v12
	v_cvt_pk_bf16_f32 v16, v23, v21
	v_cvt_pk_bf16_f32 v17, v25, v27
	v_cvt_pk_bf16_f32 v18, v29, v31
	v_cvt_pk_bf16_f32 v19, v33, v35
	ds_read2_b32 v[22:23], v11 offset0:49 offset1:57
	ds_read2_b32 v[24:25], v11 offset0:16 offset1:24
	ds_read2_b32 v[26:27], v11 offset0:82 offset1:90
	ds_read2_b32 v[28:29], v11 offset0:115 offset1:123
	ds_read2_b32 v[30:31], v11 offset0:148 offset1:156
	ds_read2_b32 v[32:33], v11 offset0:181 offset1:189
	ds_read2_b32 v[34:35], v11 offset0:214 offset1:222
	ds_read2_b32 v[38:39], v11 offset0:247 offset1:255
	v_lshl_add_u64 v[20:21], v[36:37], 0, v[12:13]
	v_or_b32_e32 v12, v40, v56
	v_lshlrev_b32_e32 v12, 11, v12
	global_store_dwordx4 v[20:21], v[16:19], off
	v_lshl_add_u64 v[20:21], v[36:37], 0, v[12:13]
	v_or_b32_e32 v12, v40, v57
	s_waitcnt lgkmcnt(6)
	v_cvt_pk_bf16_f32 v16, v24, v22
	s_waitcnt lgkmcnt(4)
	v_cvt_pk_bf16_f32 v17, v26, v28
	s_waitcnt lgkmcnt(2)
	v_cvt_pk_bf16_f32 v18, v30, v32
	s_waitcnt lgkmcnt(0)
	v_cvt_pk_bf16_f32 v19, v34, v38
	v_lshlrev_b32_e32 v12, 11, v12
	global_store_dwordx4 v[20:21], v[16:19], off
	v_lshl_add_u64 v[20:21], v[36:37], 0, v[12:13]
	s_nop 0
	v_cvt_pk_bf16_f32 v16, v25, v23
	v_cvt_pk_bf16_f32 v17, v27, v29
	v_cvt_pk_bf16_f32 v18, v31, v33
	v_cvt_pk_bf16_f32 v19, v35, v39
	global_store_dwordx4 v[20:21], v[16:19], off
	s_waitcnt lgkmcnt(0)

; #define LAS __attribute__((address_space(3)))
; __device__ __forceinline__ void transpose_item(const float* W, int ldw, const float* kgain, float scale, bf16_t* WT, int ldt, int k0, int n_src0, int n_dst0, LAS float* scr, int lane) {
;     float wv[32];
; #pragma unroll
;     for (int i = 0; i < 32; ++i) wv[i] = W[(size_t)(k0 + 2 * i + (lane >> 5)) * ldw + n_src0 + (lane & 31)];
; __device__ __forceinline__ void phase_prologue(const P& p, unsigned char* ws, LAS unsigned char* lds, int wg, int nwg) {
;     ...
;         if (r < I_UH) { transpose_item(p.w_hup + (size_t)l * HW * D, D, nullptr, 1.f, (bf16_t*)(ws + WS_WUH) + (size_t)l * D * HW, HW, (r / (D / 32)) * 64, (r % (D / 32)) * 32, (r % (D / 32)) * 32, scr, lane); continue; } r -= I_UH;
.LBB0_37:
	s_andn2_saveexec_b64 s[44:45], s[82:83]
	s_cbranch_execz .LBB0_39
	v_ashrrev_i32_e32 v21, 31, v20
	v_lshlrev_b64 v[16:17], 23, v[20:21]
	v_lshl_add_u64 v[18:19], s[34:35], 0, v[16:17]
	v_and_b32_e32 v16, 0x3fc0, v12
	v_lshlrev_b32_e32 v12, 5, v12
	v_and_b32_e32 v40, 0x7e0, v12
	v_add_u32_e32 v16, 0xffffd200, v16
	v_lshlrev_b32_e32 v12, 2, v40
	v_or_b32_e32 v22, v16, v8
	v_lshl_add_u64 v[18:19], v[18:19], 0, v[12:13]
	v_lshlrev_b32_e32 v12, 2, v10
	v_lshl_add_u64 v[18:19], v[18:19], 0, v[12:13]
	v_or_b32_e32 v12, 2, v22
	v_lshlrev_b64 v[26:27], 13, v[12:13]
	v_or_b32_e32 v12, 4, v22
	v_lshlrev_b64 v[28:29], 13, v[12:13]
	v_or_b32_e32 v12, 6, v22
	v_lshlrev_b64 v[30:31], 13, v[12:13]
	v_or_b32_e32 v12, 8, v22
	v_lshlrev_b64 v[32:33], 13, v[12:13]
	v_or_b32_e32 v12, 10, v22
	v_mov_b32_e32 v23, v13
	v_lshlrev_b64 v[34:35], 13, v[12:13]
	v_or_b32_e32 v12, 12, v22
	v_lshlrev_b64 v[24:25], 13, v[22:23]
	v_lshlrev_b64 v[36:37], 13, v[12:13]
	v_or_b32_e32 v12, 14, v22
	v_lshl_add_u64 v[24:25], v[18:19], 0, v[24:25]
	v_lshlrev_b64 v[38:39], 13, v[12:13]
	v_or_b32_e32 v12, 16, v22
	v_lshl_add_u64 v[26:27], v[18:19], 0, v[26:27]
	v_lshl_add_u64 v[28:29], v[18:19], 0, v[28:29]
	v_lshl_add_u64 v[30:31], v[18:19], 0, v[30:31]
	v_lshl_add_u64 v[32:33], v[18:19], 0, v[32:33]
	v_lshl_add_u64 v[34:35], v[18:19], 0, v[34:35]
	v_lshl_add_u64 v[36:37], v[18:19], 0, v[36:37]
	v_lshl_add_u64 v[38:39], v[18:19], 0, v[38:39]
	global_load_dword v17, v[24:25], off nt
	global_load_dword v41, v[26:27], off nt
	global_load_dword v42, v[28:29], off nt
	global_load_dword v43, v[30:31], off nt
	global_load_dword v44, v[32:33], off nt
	global_load_dword v45, v[34:35], off nt
	global_load_dword v46, v[36:37], off nt
	global_load_dword v47, v[38:39], off nt
	v_lshlrev_b64 v[24:25], 13, v[12:13]
	v_or_b32_e32 v12, 18, v22
	v_lshlrev_b64 v[26:27], 13, v[12:13]
	v_or_b32_e32 v12, 20, v22
	v_lshlrev_b64 v[28:29], 13, v[12:13]
	v_or_b32_e32 v12, 22, v22
	v_lshlrev_b64 v[30:31], 13, v[12:13]
	v_or_b32_e32 v12, 24, v22
	v_lshlrev_b64 v[32:33], 13, v[12:13]
	v_or_b32_e32 v12, 26, v22
	v_lshlrev_b64 v[34:35], 13, v[12:13]
	v_or_b32_e32 v12, 28, v22
	v_lshlrev_b64 v[36:37], 13, v[12:13]
	v_or_b32_e32 v12, 30, v22
	v_lshl_add_u64 v[24:25], v[18:19], 0, v[24:25]
	v_lshlrev_b64 v[38:39], 13, v[12:13]
	v_or_b32_e32 v12, 32, v22
	v_lshl_add_u64 v[26:27], v[18:19], 0, v[26:27]
	v_lshl_add_u64 v[28:29], v[18:19], 0, v[28:29]
	v_lshl_add_u64 v[30:31], v[18:19], 0, v[30:31]
	v_lshl_add_u64 v[32:33], v[18:19], 0, v[32:33]
	v_lshl_add_u64 v[34:35], v[18:19], 0, v[34:35]
	v_lshl_add_u64 v[36:37], v[18:19], 0, v[36:37]
	v_lshl_add_u64 v[38:39], v[18:19], 0, v[38:39]
	global_load_dword v48, v[24:25], off nt
	global_load_dword v49, v[26:27], off nt
	global_load_dword v50, v[28:29], off nt
	global_load_dword v51, v[30:31], off nt
	global_load_dword v52, v[32:33], off nt
	global_load_dword v53, v[34:35], off nt
	global_load_dword v54, v[36:37], off nt
	global_load_dword v55, v[38:39], off nt
	v_lshlrev_b64 v[24:25], 13, v[12:13]
	v_or_b32_e32 v12, 34, v22
	v_lshlrev_b64 v[26:27], 13, v[12:13]
	v_or_b32_e32 v12, 36, v22
	v_lshlrev_b64 v[28:29], 13, v[12:13]
	v_or_b32_e32 v12, 38, v22
	v_lshlrev_b64 v[30:31], 13, v[12:13]
	v_or_b32_e32 v12, 40, v22
	v_lshlrev_b64 v[32:33], 13, v[12:13]
	v_or_b32_e32 v12, 42, v22
	v_lshlrev_b64 v[34:35], 13, v[12:13]
	v_or_b32_e32 v12, 44, v22
	v_lshlrev_b64 v[36:37], 13, v[12:13]
	v_or_b32_e32 v12, 46, v22
	v_lshlrev_b64 v[38:39], 13, v[12:13]
	v_lshl_add_u64 v[24:25], v[18:19], 0, v[24:25]
	v_lshl_add_u64 v[38:39], v[18:19], 0, v[38:39]
	v_or_b32_e32 v12, 48, v22
	v_lshl_add_u64 v[26:27], v[18:19], 0, v[26:27]
	v_lshl_add_u64 v[28:29], v[18:19], 0, v[28:29]
	v_lshl_add_u64 v[30:31], v[18:19], 0, v[30:31]
	v_lshl_add_u64 v[32:33], v[18:19], 0, v[32:33]
	v_lshl_add_u64 v[34:35], v[18:19], 0, v[34:35]
	v_lshl_add_u64 v[36:37], v[18:19], 0, v[36:37]
	global_load_dword v69, v[24:25], off nt
	global_load_dword v70, v[26:27], off nt
	global_load_dword v71, v[28:29], off nt
	global_load_dword v72, v[30:31], off nt
	global_load_dword v73, v[32:33], off nt
	global_load_dword v74, v[34:35], off nt
	global_load_dword v75, v[36:37], off nt
	s_nop 0
	global_load_dword v38, v[38:39], off nt
	v_lshlrev_b64 v[24:25], 13, v[12:13]
	v_or_b32_e32 v12, 50, v22
	v_lshlrev_b64 v[26:27], 13, v[12:13]
	v_or_b32_e32 v12, 52, v22
	v_lshlrev_b64 v[28:29], 13, v[12:13]
	v_or_b32_e32 v12, 54, v22
	v_lshlrev_b64 v[30:31], 13, v[12:13]
	v_or_b32_e32 v12, 56, v22
	v_lshlrev_b64 v[32:33], 13, v[12:13]
	v_or_b32_e32 v12, 58, v22
	v_lshlrev_b64 v[34:35], 13, v[12:13]
	v_or_b32_e32 v12, 60, v22
	v_lshlrev_b64 v[36:37], 13, v[12:13]
	v_or_b32_e32 v12, 62, v22
	v_lshl_add_u64 v[24:25], v[18:19], 0, v[24:25]
	v_lshl_add_u64 v[26:27], v[18:19], 0, v[26:27]
	v_lshl_add_u64 v[28:29], v[18:19], 0, v[28:29]
	v_lshlrev_b64 v[22:23], 13, v[12:13]
	v_lshl_add_u64 v[30:31], v[18:19], 0, v[30:31]
	v_lshl_add_u64 v[32:33], v[18:19], 0, v[32:33]
	v_lshl_add_u64 v[34:35], v[18:19], 0, v[34:35]
	v_lshl_add_u64 v[36:37], v[18:19], 0, v[36:37]
	v_lshl_add_u64 v[18:19], v[18:19], 0, v[22:23]
	global_load_dword v12, v[24:25], off nt
	global_load_dword v22, v[26:27], off nt
	global_load_dword v23, v[28:29], off nt
	s_nop 0
	global_load_dword v24, v[30:31], off nt
	global_load_dword v25, v[32:33], off nt
	global_load_dword v26, v[34:35], off nt
	global_load_dword v27, v[36:37], off nt
	global_load_dword v28, v[18:19], off nt
	s_waitcnt vmcnt(30)
; #define LAS __attribute__((address_space(3)))
; __device__ __forceinline__ unsigned pk2(float lo, float hi) { return pg8::cvt_pk_bf16(lo, hi); }
; __device__ __forceinline__ void transpose_item(const float* W, int ldw, const float* kgain, float scale, bf16_t* WT, int ldt, int k0, int n_src0, int n_dst0, LAS float* scr, int lane) {
;     ...
;     for (int i = 0; i < 32; ++i) scr[(2 * i + (lane >> 5)) * 33 + (lane & 31)] = wv[i];
;     asm volatile("s_waitcnt lgkmcnt(0)" ::: "memory");
;     const int c = lane & 7;
; #pragma unroll
;     for (int j = 0; j < 4; ++j) { const int n = (lane >> 3) + 8 * j; const LAS float* s = scr + (8 * c) * 33 + n;
;         u32x4 o; o.x = pk2(s[0 * 33], s[1 * 33]); o.y = pk2(s[2 * 33], s[3 * 33]); o.z = pk2(s[4 * 33], s[5 * 33]); o.w = pk2(s[6 * 33], s[7 * 33]);
;         *(u32x4*)(WT + (size_t)(n_dst0 + n) * ldt + k0 + 8 * c) = o; }
;     asm volatile("s_waitcnt lgkmcnt(0)" ::: "memory");
	ds_write2_b32 v5, v17, v41 offset1:66
	s_waitcnt vmcnt(28)
	ds_write2_b32 v5, v42, v43 offset0:132 offset1:198
	v_add_u32_e32 v17, 0x400, v5
	s_waitcnt vmcnt(26)
	ds_write2_b32 v17, v44, v45 offset0:8 offset1:74
	s_waitcnt vmcnt(24)
	ds_write2_b32 v17, v46, v47 offset0:140 offset1:206
	v_add_u32_e32 v17, 0x800, v5
	s_waitcnt vmcnt(22)
	ds_write2_b32 v17, v48, v49 offset0:16 offset1:82
	s_waitcnt vmcnt(20)
	ds_write2_b32 v17, v50, v51 offset0:148 offset1:214
	v_add_u32_e32 v17, 0xc00, v5
	s_waitcnt vmcnt(18)
	ds_write2_b32 v17, v52, v53 offset0:24 offset1:90
	s_waitcnt vmcnt(16)
	ds_write2_b32 v17, v54, v55 offset0:156 offset1:222
	v_add_u32_e32 v17, 0x1000, v5
	s_waitcnt vmcnt(14)
	ds_write2_b32 v17, v69, v70 offset0:32 offset1:98
	s_waitcnt vmcnt(12)
	ds_write2_b32 v17, v71, v72 offset0:164 offset1:230
	v_add_u32_e32 v17, 0x1400, v5
	s_waitcnt vmcnt(10)
	ds_write2_b32 v17, v73, v74 offset0:40 offset1:106
	s_waitcnt vmcnt(8)
	ds_write2_b32 v17, v75, v38 offset0:172 offset1:238
	v_add_u32_e32 v17, 0x1800, v5
	s_waitcnt vmcnt(6)
	ds_write2_b32 v17, v12, v22 offset0:48 offset1:114
	s_waitcnt vmcnt(4)
	ds_write2_b32 v17, v23, v24 offset0:180 offset1:246
	v_add_u32_e32 v12, 0x1c00, v5
	s_waitcnt vmcnt(2)
	ds_write2_b32 v12, v25, v26 offset0:56 offset1:122
	s_waitcnt vmcnt(0)
	ds_write2_b32 v12, v27, v28 offset0:188 offset1:254
	s_waitcnt lgkmcnt(0)
	v_lshlrev_b64 v[18:19], 22, v[20:21]
	ds_read2_b32 v[20:21], v11 offset0:33 offset1:41
	ds_read2_b32 v[22:23], v11 offset1:8
	ds_read2_b32 v[24:25], v11 offset0:66 offset1:74
	ds_read2_b32 v[26:27], v11 offset0:99 offset1:107
	ds_read2_b32 v[28:29], v11 offset0:132 offset1:140
	ds_read2_b32 v[30:31], v11 offset0:165 offset1:173
	ds_read2_b32 v[32:33], v11 offset0:198 offset1:206
	ds_read2_b32 v[34:35], v11 offset0:231 offset1:239
	v_lshl_add_u64 v[18:19], s[68:69], 0, v[18:19]
	v_mov_b32_e32 v17, v13
	v_lshl_add_u64 v[16:17], v[16:17], 1, v[18:19]
	v_lshlrev_b32_e32 v12, 1, v14
	v_lshl_add_u64 v[36:37], v[16:17], 0, v[12:13]
	v_or_b32_e32 v12, v40, v7
	v_lshlrev_b32_e32 v12, 11, v12
	s_waitcnt lgkmcnt(6)
	v_cvt_pk_bf16_f32 v16, v22, v20
	s_waitcnt lgkmcnt(4)
	v_cvt_pk_bf16_f32 v17, v24, v26
	s_waitcnt lgkmcnt(2)
	v_cvt_pk_bf16_f32 v18, v28, v30
	s_waitcnt lgkmcnt(0)
	v_cvt_pk_bf16_f32 v19, v32, v34
	v_lshl_add_u64 v[38:39], v[36:37], 0, v[12:13]
	global_store_dwordx4 v[38:39], v[16:19], off
	v_or_b32_e32 v12, v40, v15
	v_lshlrev_b32_e32 v12, 11, v12
	v_cvt_pk_bf16_f32 v16, v23, v21
	v_cvt_pk_bf16_f32 v17, v25, v27
	v_cvt_pk_bf16_f32 v18, v29, v31
	v_cvt_pk_bf16_f32 v19, v33, v35
	ds_read2_b32 v[22:23], v11 offset0:49 offset1:57
	ds_read2_b32 v[24:25], v11 offset0:16 offset1:24
	ds_read2_b32 v[26:27], v11 offset0:82 offset1:90
	ds_read2_b32 v[28:29], v11 offset0:115 offset1:123
	ds_read2_b32 v[30:31], v11 offset0:148 offset1:156
	ds_read2_b32 v[32:33], v11 offset0:181 offset1:189
	ds_read2_b32 v[34:35], v11 offset0:214 offset1:222
	ds_read2_b32 v[38:39], v11 offset0:247 offset1:255
	v_lshl_add_u64 v[20:21], v[36:37], 0, v[12:13]
	v_or_b32_e32 v12, v40, v56
	v_lshlrev_b32_e32 v12, 11, v12
	global_store_dwordx4 v[20:21], v[16:19], off
	v_lshl_add_u64 v[20:21], v[36:37], 0, v[12:13]
	v_or_b32_e32 v12, v40, v57
	s_waitcnt lgkmcnt(6)
	v_cvt_pk_bf16_f32 v16, v24, v22
	s_waitcnt lgkmcnt(4)
	v_cvt_pk_bf16_f32 v17, v26, v28
	s_waitcnt lgkmcnt(2)
	v_cvt_pk_bf16_f32 v18, v30, v32
	s_waitcnt lgkmcnt(0)
	v_cvt_pk_bf16_f32 v19, v34, v38
	v_lshlrev_b32_e32 v12, 11, v12
	global_store_dwordx4 v[20:21], v[16:19], off
	v_lshl_add_u64 v[20:21], v[36:37], 0, v[12:13]
	s_nop 0
	v_cvt_pk_bf16_f32 v16, v25, v23
	v_cvt_pk_bf16_f32 v17, v27, v29
	v_cvt_pk_bf16_f32 v18, v31, v33
	v_cvt_pk_bf16_f32 v19, v35, v39
	global_store_dwordx4 v[20:21], v[16:19], off
	s_waitcnt lgkmcnt(0)

; __device__ __forceinline__ void transpose_item(const float* W, int ldw, const float* kgain, float scale, bf16_t* WT, int ldt, int k0, int n_src0, int n_dst0, LAS float* scr, int lane) {
;     float wv[32];
; #pragma unroll
;     for (int i = 0; i < 32; ++i) wv[i] = W[(size_t)(k0 + 2 * i + (lane >> 5)) * ldw + n_src0 + (lane & 31)];
; __device__ __forceinline__ void phase_prologue(const P& p, unsigned char* ws, LAS unsigned char* lds, int wg, int nwg) {
;     ...
;         if (r < I_IN) { const int nb = r % (NZ / 32), kb = r / (NZ / 32), n0 = nb * 32; bf16_t* WT = (bf16_t*)(ws + WS_WIN) + (size_t)l * NZ * D; const float* Win = p.w_in + (size_t)l * D * NIN; const float* kg = p.n_pre_mix + l * D;
;             if (n0 >= 7168 && n0 < 7680) fold_item(Win, p.wgg + (size_t)l * GR * GKW, kg, WT, kb * 64, n0 - 7168, n0, scr, lane);
;             else { const int ns = n0 < 7168 ? n0 : n0 - 496; const float sc = (n0 >= 4096 && n0 < 4608) ? 0.08838834764831845f : 1.f; transpose_item(Win, NIN, kg, sc, WT, D, kb * 64, ns, n0, scr, lane); }
.LBB0_40:
	s_andn2_saveexec_b64 s[80:81], s[80:81]
	s_cbranch_execz .LBB0_11
	s_mov_b32 s33, 0xb21642c9
	v_mul_hi_i32 v16, v12, s33
	v_add_u32_e32 v16, v16, v12
	v_lshrrev_b32_e32 v17, 31, v16
	v_ashrrev_i32_e32 v16, 8, v16
	v_add_u32_e32 v18, v16, v17
	v_mul_i32_i24_e32 v16, 0x170, v18
	v_sub_u32_e32 v12, v12, v16
	v_mov_b64_e32 v[16:17], s[70:71]
	s_mov_b32 s33, 0x2e00000
	v_mad_i64_i32 v[16:17], s[44:45], v20, s33, v[16:17]
	s_mov_b32 s33, 0x5820000
	v_lshlrev_b32_e32 v52, 11, v20
	v_and_b32_e32 v19, -16, v12
	v_lshlrev_b32_e32 v69, 5, v12
	v_mad_i64_i32 v[54:55], s[44:45], v20, s33, 0
	v_ashrrev_i32_e32 v53, 31, v52
	v_cmp_ne_u32_e32 vcc, s7, v19
	v_lshlrev_b32_e32 v18, 6, v18
	s_and_saveexec_b64 s[44:45], vcc
	s_xor_b64 s[44:45], exec, s[44:45]
	s_cbranch_execz .LBB0_45
	v_add_u32_e32 v22, 0xfffffe10, v69
	v_cmp_gt_i32_e32 vcc, s7, v12
	v_lshl_add_u64 v[20:21], s[30:31], 0, v[54:55]
	v_or_b32_e32 v54, v18, v8
	v_cndmask_b32_e32 v22, v22, v69, vcc
	v_ashrrev_i32_e32 v23, 31, v22
	v_lshl_add_u64 v[20:21], v[22:23], 2, v[20:21]
	v_lshlrev_b32_e32 v12, 2, v10
	v_lshl_add_u64 v[44:45], v[20:21], 0, v[12:13]
	v_or_b32_e32 v12, 2, v54
	v_mad_i64_i32 v[22:23], s[50:51], v12, s15, v[44:45]
	v_or_b32_e32 v12, 4, v54
	v_mad_i64_i32 v[24:25], s[50:51], v12, s15, v[44:45]
	v_or_b32_e32 v12, 6, v54
	v_mad_i64_i32 v[26:27], s[50:51], v12, s15, v[44:45]
	v_or_b32_e32 v12, 8, v54
	v_mad_i64_i32 v[28:29], s[50:51], v12, s15, v[44:45]
	v_or_b32_e32 v12, 10, v54
	v_mad_i64_i32 v[30:31], s[50:51], v12, s15, v[44:45]
	v_or_b32_e32 v12, 12, v54
	v_mad_i64_i32 v[32:33], s[50:51], v12, s15, v[44:45]
	v_or_b32_e32 v12, 14, v54
	v_mad_i64_i32 v[20:21], s[50:51], v54, s15, v[44:45]
	v_mad_i64_i32 v[34:35], s[50:51], v12, s15, v[44:45]
	v_or_b32_e32 v12, 16, v54
	global_load_dword v20, v[20:21], off nt
	s_nop 0
	global_load_dword v21, v[22:23], off nt
	s_nop 0
	global_load_dword v22, v[24:25], off nt
	global_load_dword v23, v[26:27], off nt
	s_nop 0
	global_load_dword v24, v[28:29], off nt
	global_load_dword v25, v[30:31], off nt
	global_load_dword v26, v[32:33], off nt
	global_load_dword v27, v[34:35], off nt
	v_mad_i64_i32 v[28:29], s[50:51], v12, s15, v[44:45]
	v_or_b32_e32 v12, 18, v54
	v_mad_i64_i32 v[30:31], s[50:51], v12, s15, v[44:45]
	v_or_b32_e32 v12, 20, v54
	v_mad_i64_i32 v[32:33], s[50:51], v12, s15, v[44:45]
	v_or_b32_e32 v12, 22, v54
	v_mad_i64_i32 v[34:35], s[50:51], v12, s15, v[44:45]
	v_or_b32_e32 v12, 24, v54
	v_mad_i64_i32 v[36:37], s[50:51], v12, s15, v[44:45]
	v_or_b32_e32 v12, 26, v54
	v_mad_i64_i32 v[38:39], s[50:51], v12, s15, v[44:45]
	v_or_b32_e32 v12, 28, v54
	v_mad_i64_i32 v[40:41], s[50:51], v12, s15, v[44:45]
	v_or_b32_e32 v12, 30, v54
	v_mad_i64_i32 v[42:43], s[50:51], v12, s15, v[44:45]
	v_or_b32_e32 v12, 32, v54
	global_load_dword v28, v[28:29], off nt
	s_nop 0
	global_load_dword v29, v[30:31], off nt
	s_nop 0
	global_load_dword v30, v[32:33], off nt
	global_load_dword v31, v[34:35], off nt
	s_nop 0
	global_load_dword v32, v[36:37], off nt
	global_load_dword v33, v[38:39], off nt
	global_load_dword v34, v[40:41], off nt
	global_load_dword v35, v[42:43], off nt
	v_mad_i64_i32 v[36:37], s[50:51], v12, s15, v[44:45]
	v_or_b32_e32 v12, 34, v54
	v_mad_i64_i32 v[38:39], s[50:51], v12, s15, v[44:45]
	v_or_b32_e32 v12, 36, v54
	v_mad_i64_i32 v[40:41], s[50:51], v12, s15, v[44:45]
	v_or_b32_e32 v12, 38, v54
	v_mad_i64_i32 v[42:43], s[50:51], v12, s15, v[44:45]
	v_or_b32_e32 v12, 40, v54
	v_mad_i64_i32 v[46:47], s[50:51], v12, s15, v[44:45]
	v_or_b32_e32 v12, 42, v54
	v_mad_i64_i32 v[48:49], s[50:51], v12, s15, v[44:45]
	v_or_b32_e32 v12, 44, v54
	v_mad_i64_i32 v[50:51], s[50:51], v12, s15, v[44:45]
	v_or_b32_e32 v12, 46, v54
	v_mad_i64_i32 v[70:71], s[50:51], v12, s15, v[44:45]
	v_or_b32_e32 v12, 48, v54
	global_load_dword v36, v[36:37], off nt
	s_nop 0
	global_load_dword v37, v[38:39], off nt
	s_nop 0
	global_load_dword v38, v[40:41], off nt
	global_load_dword v39, v[42:43], off nt
	s_nop 0
	global_load_dword v40, v[46:47], off nt
	global_load_dword v41, v[48:49], off nt
	global_load_dword v42, v[50:51], off nt
	global_load_dword v43, v[70:71], off nt
	v_mad_i64_i32 v[46:47], s[50:51], v12, s15, v[44:45]
	v_or_b32_e32 v12, 50, v54
	v_mad_i64_i32 v[48:49], s[50:51], v12, s15, v[44:45]
	v_or_b32_e32 v12, 52, v54
	v_mad_i64_i32 v[50:51], s[50:51], v12, s15, v[44:45]
	v_or_b32_e32 v12, 54, v54
	v_mad_i64_i32 v[70:71], s[50:51], v12, s15, v[44:45]
	v_or_b32_e32 v12, 56, v54
	v_mad_i64_i32 v[72:73], s[50:51], v12, s15, v[44:45]
	v_or_b32_e32 v12, 58, v54
	v_mad_i64_i32 v[74:75], s[50:51], v12, s15, v[44:45]
	v_or_b32_e32 v12, 60, v54
	v_mad_i64_i32 v[76:77], s[50:51], v12, s15, v[44:45]
	v_or_b32_e32 v12, 62, v54
	v_mad_i64_i32 v[78:79], s[50:51], v12, s15, v[44:45]
	global_load_dword v44, v[46:47], off nt
	global_load_dword v45, v[48:49], off nt
	s_nop 0
	global_load_dword v46, v[50:51], off nt
	global_load_dword v47, v[70:71], off nt
	global_load_dword v48, v[72:73], off nt
	global_load_dword v49, v[74:75], off nt
	s_nop 0
	global_load_dword v50, v[76:77], off nt
	global_load_dword v51, v[78:79], off nt
	s_andn2_b64 vcc, exec, s[76:77]
	s_cbranch_vccnz .LBB0_44
; __device__ __forceinline__ void transpose_item(const float* W, int ldw, const float* kgain, float scale, bf16_t* WT, int ldt, int k0, int n_src0, int n_dst0, LAS float* scr, int lane) {
;     ...
;     if (kgain) {
; #pragma unroll
;         for (int i = 0; i < 32; ++i) wv[i] *= kgain[k0 + 2 * i + (lane >> 5)] * scale; }
	v_ashrrev_i32_e32 v55, 31, v54
	v_lshl_add_u64 v[52:53], v[52:53], 2, s[0:1]
	v_lshl_add_u64 v[52:53], v[54:55], 2, v[52:53]
	global_load_dword v54, v[52:53], off nt
	global_load_dword v55, v[52:53], off offset:8
	global_load_dword v70, v[52:53], off offset:16
	global_load_dword v71, v[52:53], off offset:24
	global_load_dword v72, v[52:53], off offset:32
	global_load_dword v73, v[52:53], off offset:40
	global_load_dword v74, v[52:53], off offset:48
	global_load_dword v75, v[52:53], off offset:56
	global_load_dword v76, v[52:53], off offset:64
	global_load_dword v77, v[52:53], off offset:72
	global_load_dword v78, v[52:53], off offset:80
	global_load_dword v79, v[52:53], off offset:88
	global_load_dword v80, v[52:53], off offset:96
	global_load_dword v81, v[52:53], off offset:104
	global_load_dword v82, v[52:53], off offset:112
	global_load_dword v83, v[52:53], off offset:120
	global_load_dword v84, v[52:53], off offset:128
	global_load_dword v85, v[52:53], off offset:136
	global_load_dword v86, v[52:53], off offset:144
	global_load_dword v87, v[52:53], off offset:152
	global_load_dword v88, v[52:53], off offset:160
	global_load_dword v89, v[52:53], off offset:168
	global_load_dword v90, v[52:53], off offset:176
	global_load_dword v91, v[52:53], off offset:184
	global_load_dword v92, v[52:53], off offset:192
	global_load_dword v93, v[52:53], off offset:200
	global_load_dword v94, v[52:53], off offset:208
	global_load_dword v95, v[52:53], off offset:216
	global_load_dword v96, v[52:53], off offset:224
	global_load_dword v97, v[52:53], off offset:232
	global_load_dword v98, v[52:53], off offset:240
	global_load_dword v99, v[52:53], off offset:248
	v_cmp_eq_u32_e32 vcc, s23, v19
	s_nop 1
	v_cndmask_b32_e32 v12, 1.0, v67, vcc
	s_waitcnt vmcnt(30)
	v_pk_mul_f32 v[52:53], v[12:13], v[54:55] op_sel_hi:[0,1]
	v_pk_mul_f32 v[20:21], v[20:21], v[52:53]
	s_waitcnt vmcnt(28)
	v_pk_mul_f32 v[54:55], v[12:13], v[70:71] op_sel_hi:[0,1]
	v_pk_mul_f32 v[22:23], v[22:23], v[54:55]
	s_waitcnt vmcnt(26)
	v_pk_mul_f32 v[70:71], v[12:13], v[72:73] op_sel_hi:[0,1]
	v_pk_mul_f32 v[24:25], v[24:25], v[70:71]
	s_waitcnt vmcnt(24)
	v_pk_mul_f32 v[72:73], v[12:13], v[74:75] op_sel_hi:[0,1]
	v_pk_mul_f32 v[26:27], v[26:27], v[72:73]
	s_waitcnt vmcnt(22)
	v_pk_mul_f32 v[74:75], v[12:13], v[76:77] op_sel_hi:[0,1]
	v_pk_mul_f32 v[28:29], v[28:29], v[74:75]
	s_waitcnt vmcnt(20)
	v_pk_mul_f32 v[76:77], v[12:13], v[78:79] op_sel_hi:[0,1]
	v_pk_mul_f32 v[30:31], v[30:31], v[76:77]
	s_waitcnt vmcnt(18)
	v_pk_mul_f32 v[78:79], v[12:13], v[80:81] op_sel_hi:[0,1]
	v_pk_mul_f32 v[32:33], v[32:33], v[78:79]
	s_waitcnt vmcnt(16)
	v_pk_mul_f32 v[80:81], v[12:13], v[82:83] op_sel_hi:[0,1]
	v_pk_mul_f32 v[34:35], v[34:35], v[80:81]
	s_waitcnt vmcnt(14)
	v_pk_mul_f32 v[82:83], v[12:13], v[84:85] op_sel_hi:[0,1]
	v_pk_mul_f32 v[36:37], v[36:37], v[82:83]
	s_waitcnt vmcnt(12)
	v_pk_mul_f32 v[84:85], v[12:13], v[86:87] op_sel_hi:[0,1]
	v_pk_mul_f32 v[38:39], v[38:39], v[84:85]
	s_waitcnt vmcnt(10)
	v_pk_mul_f32 v[86:87], v[12:13], v[88:89] op_sel_hi:[0,1]
	v_pk_mul_f32 v[40:41], v[40:41], v[86:87]
	s_waitcnt vmcnt(8)
	v_pk_mul_f32 v[88:89], v[12:13], v[90:91] op_sel_hi:[0,1]
	v_pk_mul_f32 v[42:43], v[42:43], v[88:89]
	s_waitcnt vmcnt(6)
	v_pk_mul_f32 v[90:91], v[12:13], v[92:93] op_sel_hi:[0,1]
	v_pk_mul_f32 v[44:45], v[44:45], v[90:91]
	s_waitcnt vmcnt(4)
	v_pk_mul_f32 v[92:93], v[12:13], v[94:95] op_sel_hi:[0,1]
	v_pk_mul_f32 v[46:47], v[46:47], v[92:93]
	s_waitcnt vmcnt(2)
	v_pk_mul_f32 v[94:95], v[12:13], v[96:97] op_sel_hi:[0,1]
	v_pk_mul_f32 v[48:49], v[48:49], v[94:95]
	s_waitcnt vmcnt(0)
	v_pk_mul_f32 v[96:97], v[12:13], v[98:99] op_sel_hi:[0,1]
	v_pk_mul_f32 v[50:51], v[50:51], v[96:97]

; __device__ __forceinline__ void fold_item(const float* Win, const float* wgg, const float* kgain, bf16_t* WT, int k0, int j0, int n_dst0, LAS float* scr, int lane) {
;     float wg[GR];
; #pragma unroll
;     for (int r = 0; r < GR; ++r) wg[r] = wgg[r * GKW + j0 + (lane & 31)];
; #pragma unroll 8
;     for (int i = 0; i < 32; ++i) { const int kk = 2 * i + (lane >> 5); const f32x4* wr = (const f32x4*)(Win + (size_t)(k0 + kk) * NIN + C_GLR); float s = 0.f;
; #pragma unroll
;         for (int r4 = 0; r4 < GR / 4; ++r4) { const f32x4 x = wr[r4]; s += (x[0] * wg[4 * r4] + x[1] * wg[4 * r4 + 1]) + (x[2] * wg[4 * r4 + 2] + x[3] * wg[4 * r4 + 3]); }
;         scr[kk * 33 + (lane & 31)] = s * kgain[k0 + kk]; }
.LBB0_45:
	s_andn2_saveexec_b64 s[82:83], s[44:45]
	s_cbranch_execz .LBB0_10
	v_ashrrev_i32_e32 v21, 31, v20
	v_lshlrev_b64 v[20:21], 15, v[20:21]
	v_lshl_add_u64 v[20:21], s[36:37], 0, v[20:21]
	v_add_u32_e32 v12, v58, v69
	v_lshl_add_u64 v[28:29], v[12:13], 2, v[20:21]
	v_add_co_u32_e32 v24, vcc, 0x1000, v28
	v_lshlrev_b64 v[46:47], 2, v[52:53]
	s_nop 0
	v_addc_co_u32_e32 v25, vcc, 0, v29, vcc
	v_add_co_u32_e32 v26, vcc, 0x2000, v28
	v_add_u32_e32 v52, v8, v18
	s_nop 0
	v_addc_co_u32_e32 v27, vcc, 0, v29, vcc
	v_add_co_u32_e32 v30, vcc, 0x3000, v28
	v_ashrrev_i32_e32 v19, 31, v18
	s_nop 0
	v_addc_co_u32_e32 v31, vcc, 0, v29, vcc
	global_load_dword v20, v[28:29], off nt
	global_load_dword v22, v[28:29], off offset:2048
	global_load_dword v23, v[24:25], off nt
	global_load_dword v21, v[24:25], off offset:2048
	s_nop 0
	global_load_dword v24, v[26:27], off nt
	s_nop 0
	global_load_dword v26, v[26:27], off offset:2048
	s_nop 0
	global_load_dword v27, v[30:31], off nt
	global_load_dword v25, v[30:31], off offset:2048
	v_add_co_u32_e32 v30, vcc, 0x4000, v28
	v_add_u32_e32 v38, v63, v18
	s_nop 0
	v_addc_co_u32_e32 v31, vcc, 0, v29, vcc
	v_add_co_u32_e32 v32, vcc, 0x5000, v28
	v_add_u32_e32 v40, v64, v18
	s_nop 0
	v_addc_co_u32_e32 v33, vcc, 0, v29, vcc
	v_add_co_u32_e32 v34, vcc, 0x6000, v28
	v_add_u32_e32 v42, v65, v18
	s_nop 0
	v_addc_co_u32_e32 v35, vcc, 0, v29, vcc
	v_add_co_u32_e32 v36, vcc, 0x7000, v28
	v_add_u32_e32 v44, v66, v18
	s_nop 0
	v_addc_co_u32_e32 v37, vcc, 0, v29, vcc
	global_load_dword v28, v[30:31], off nt
	global_load_dword v29, v[30:31], off offset:2048
	s_nop 0
	global_load_dword v30, v[32:33], off nt
	global_load_dword v31, v[32:33], off offset:2048
	global_load_dword v12, v[34:35], off nt
	global_load_dword v70, v[34:35], off offset:2048
	global_load_dword v71, v[36:37], off nt
	global_load_dword v72, v[36:37], off offset:2048
	v_add_u32_e32 v32, v60, v18
	v_add_u32_e32 v34, v61, v18
	v_add_u32_e32 v36, v62, v18
	v_ashrrev_i32_e32 v53, 31, v52
	v_lshl_add_u64 v[48:49], v[8:9], 0, v[18:19]
	v_mad_i64_i32 v[32:33], s[44:45], v32, s15, v[54:55]
	v_mad_i64_i32 v[34:35], s[44:45], v34, s15, v[54:55]
	v_mad_i64_i32 v[36:37], s[44:45], v36, s15, v[54:55]
	v_mad_i64_i32 v[38:39], s[44:45], v38, s15, v[54:55]
	v_mad_i64_i32 v[40:41], s[44:45], v40, s15, v[54:55]
	v_mad_i64_i32 v[42:43], s[44:45], v42, s15, v[54:55]
	v_mad_i64_i32 v[44:45], s[44:45], v44, s15, v[54:55]
	v_lshl_add_u64 v[50:51], v[52:53], 2, s[0:1]
	v_mad_i64_i32 v[52:53], s[44:45], v52, s15, v[54:55]
	v_lshl_add_u64 v[32:33], s[30:31], 0, v[32:33]
	v_lshl_add_u64 v[34:35], s[30:31], 0, v[34:35]
	v_lshl_add_u64 v[36:37], s[30:31], 0, v[36:37]
	v_lshl_add_u64 v[38:39], s[30:31], 0, v[38:39]
	v_lshl_add_u64 v[40:41], s[30:31], 0, v[40:41]
	v_lshl_add_u64 v[42:43], s[30:31], 0, v[42:43]
	v_lshl_add_u64 v[44:45], s[30:31], 0, v[44:45]
	v_lshl_add_u64 v[48:49], v[48:49], 2, s[0:1]
	v_lshl_add_u64 v[52:53], s[30:31], 0, v[52:53]
	s_mov_b64 s[84:85], 0
	v_mov_b32_e32 v73, v59
.LBB0_47:
	v_lshl_add_u64 v[54:55], v[52:53], 0, s[84:85]
	v_lshl_add_u64 v[86:87], v[54:55], 0, s[78:79]
	v_add_co_u32_e32 v54, vcc, 0x7000, v54
	s_nop 1
	v_addc_co_u32_e32 v55, vcc, 0, v55, vcc
	global_load_dwordx4 v[74:77], v[54:55], off
	global_load_dwordx4 v[78:81], v[86:87], off offset:32
	global_load_dwordx4 v[82:85], v[86:87], off offset:48
	s_nop 0
	global_load_dwordx4 v[86:89], v[86:87], off offset:16
	s_waitcnt vmcnt(3)
	v_mov_b32_e32 v54, v75
	v_mov_b32_e32 v75, v77
	v_mov_b32_e32 v55, v76
	v_pk_mul_f32 v[74:75], v[20:21], v[74:75]
	s_nop 0
	v_pk_fma_f32 v[54:55], v[22:23], v[54:55], v[74:75]
	s_waitcnt vmcnt(0)
	v_mov_b32_e32 v74, v87
	v_mov_b32_e32 v87, v89
	v_mov_b32_e32 v75, v88
	v_pk_mul_f32 v[76:77], v[24:25], v[86:87]
	v_add_f32_e32 v54, v54, v55
	v_pk_fma_f32 v[74:75], v[26:27], v[74:75], v[76:77]
	v_mul_f32_e32 v76, v70, v83
	v_pk_add_f32 v[74:75], v[74:75], v[74:75] op_sel:[0,1] op_sel_hi:[1,0]
	v_add_f32_e32 v54, 0, v54
	v_mul_f32_e32 v55, v12, v82
	v_mov_b32_e32 v75, v76
	v_pk_add_f32 v[54:55], v[54:55], v[74:75]
	v_mul_f32_e32 v74, v29, v79
	v_mul_f32_e32 v77, v71, v84
	v_pk_fma_f32 v[74:75], v[28:29], v[78:79], v[74:75] op_sel_hi:[1,1,0]
	v_mul_f32_e32 v76, v31, v81
	v_mul_f32_e32 v82, v72, v85
	v_mov_b32_e32 v75, v77
	v_pk_fma_f32 v[76:77], v[30:31], v[80:81], v[76:77] op_sel_hi:[1,1,0]
	s_nop 0
	v_mov_b32_e32 v77, v82
	v_pk_add_f32 v[74:75], v[74:75], v[76:77]
	s_nop 0
	v_pk_add_f32 v[54:55], v[54:55], v[74:75]
	s_nop 0
	v_add_f32_e32 v74, v54, v55
	v_lshl_add_u64 v[54:55], v[50:51], 0, v[46:47]
	global_load_dword v54, v[54:55], off nt
	v_lshl_add_u64 v[50:51], v[50:51], 0, 64
	s_waitcnt vmcnt(0)
	v_mul_f32_e32 v90, v54, v74
	v_lshl_add_u64 v[54:55], v[44:45], 0, s[84:85]
	v_lshl_add_u64 v[86:87], v[54:55], 0, s[78:79]
	v_add_co_u32_e32 v54, vcc, s25, v54
	s_nop 1
	v_addc_co_u32_e32 v55, vcc, 0, v55, vcc
	global_load_dwordx4 v[74:77], v[54:55], off
	global_load_dwordx4 v[78:81], v[86:87], off offset:32
	global_load_dwordx4 v[82:85], v[86:87], off offset:48
	s_nop 0
	global_load_dwordx4 v[86:89], v[86:87], off offset:16
	s_waitcnt vmcnt(3)
	v_mov_b32_e32 v54, v75
	v_mov_b32_e32 v75, v77
	v_mov_b32_e32 v55, v76
	v_pk_mul_f32 v[74:75], v[20:21], v[74:75]
	s_nop 0
	v_pk_fma_f32 v[54:55], v[22:23], v[54:55], v[74:75]
	s_waitcnt vmcnt(0)
; __device__ __forceinline__ void fold_item(const float* Win, const float* wgg, const float* kgain, bf16_t* WT, int k0, int j0, int n_dst0, LAS float* scr, int lane) {
;     ...
;     for (int i = 0; i < 32; ++i) { const int kk = 2 * i + (lane >> 5); const f32x4* wr = (const f32x4*)(Win + (size_t)(k0 + kk) * NIN + C_GLR); float s = 0.f;
; #pragma unroll
;         for (int r4 = 0; r4 < GR / 4; ++r4) { const f32x4 x = wr[r4]; s += (x[0] * wg[4 * r4] + x[1] * wg[4 * r4 + 1]) + (x[2] * wg[4 * r4 + 2] + x[3] * wg[4 * r4 + 3]); }
;         scr[kk * 33 + (lane & 31)] = s * kgain[k0 + kk]; }
	v_mov_b32_e32 v74, v87
	v_mov_b32_e32 v87, v89
	v_mov_b32_e32 v75, v88
	v_pk_mul_f32 v[76:77], v[24:25], v[86:87]
	v_add_f32_e32 v54, v54, v55
	v_pk_fma_f32 v[74:75], v[26:27], v[74:75], v[76:77]
	v_mul_f32_e32 v76, v70, v83
	v_pk_add_f32 v[74:75], v[74:75], v[74:75] op_sel:[0,1] op_sel_hi:[1,0]
	v_add_f32_e32 v54, 0, v54
	v_mul_f32_e32 v55, v12, v82
	v_mov_b32_e32 v75, v76
	v_pk_add_f32 v[54:55], v[54:55], v[74:75]
	v_mul_f32_e32 v74, v29, v79
	v_mul_f32_e32 v77, v71, v84
	v_pk_fma_f32 v[74:75], v[28:29], v[78:79], v[74:75] op_sel_hi:[1,1,0]
	v_mul_f32_e32 v76, v31, v81
	v_mul_f32_e32 v82, v72, v85
	v_mov_b32_e32 v75, v77
	v_pk_fma_f32 v[76:77], v[30:31], v[80:81], v[76:77] op_sel_hi:[1,1,0]
	s_nop 0
	v_mov_b32_e32 v77, v82
	v_pk_add_f32 v[74:75], v[74:75], v[76:77]
	s_nop 0
	v_pk_add_f32 v[54:55], v[54:55], v[74:75]
	s_nop 0
	v_add_f32_e32 v74, v54, v55
	v_lshl_add_u64 v[54:55], v[48:49], 0, v[46:47]
	global_load_dword v75, v[54:55], off offset:8
	v_lshl_add_u64 v[48:49], v[48:49], 0, 64
	s_waitcnt vmcnt(0)
	v_mul_f32_e32 v74, v75, v74
	ds_write2_b32 v73, v90, v74 offset1:66
	v_lshl_add_u64 v[74:75], v[42:43], 0, s[84:85]
	v_lshl_add_u64 v[86:87], v[74:75], 0, s[78:79]
	v_add_co_u32_e32 v74, vcc, s25, v74
	s_nop 1
	v_addc_co_u32_e32 v75, vcc, 0, v75, vcc
	global_load_dwordx4 v[74:77], v[74:75], off
	s_nop 0
	global_load_dwordx4 v[78:81], v[86:87], off offset:32
	global_load_dwordx4 v[82:85], v[86:87], off offset:48
	s_nop 0
	global_load_dwordx4 v[86:89], v[86:87], off offset:16
	s_waitcnt vmcnt(3)
	v_mov_b32_e32 v90, v75
	v_mov_b32_e32 v91, v76
	v_mov_b32_e32 v75, v77
	s_waitcnt vmcnt(0)
	v_mov_b32_e32 v76, v87
	v_mov_b32_e32 v87, v89
	v_pk_mul_f32 v[74:75], v[20:21], v[74:75]
	v_mov_b32_e32 v77, v88
	v_pk_mul_f32 v[86:87], v[24:25], v[86:87]
	v_pk_fma_f32 v[74:75], v[22:23], v[90:91], v[74:75]
	v_pk_fma_f32 v[76:77], v[26:27], v[76:77], v[86:87]
	v_add_f32_e32 v74, v74, v75
	v_mul_f32_e32 v75, v12, v82
	v_mul_f32_e32 v82, v70, v83
	v_pk_add_f32 v[76:77], v[76:77], v[76:77] op_sel:[0,1] op_sel_hi:[1,0]
	v_add_f32_e32 v74, 0, v74
	v_mov_b32_e32 v77, v82
	v_pk_add_f32 v[74:75], v[74:75], v[76:77]
	v_mul_f32_e32 v76, v29, v79
	v_pk_fma_f32 v[76:77], v[28:29], v[78:79], v[76:77] op_sel_hi:[1,1,0]
	v_mul_f32_e32 v78, v31, v81
	v_mul_f32_e32 v83, v71, v84
	v_mul_f32_e32 v84, v72, v85
	v_pk_fma_f32 v[78:79], v[30:31], v[80:81], v[78:79] op_sel_hi:[1,1,0]
	v_mov_b32_e32 v77, v83
	v_mov_b32_e32 v79, v84
	v_pk_add_f32 v[76:77], v[76:77], v[78:79]
	s_nop 0
	v_pk_add_f32 v[74:75], v[74:75], v[76:77]
	s_nop 0
	v_add_f32_e32 v74, v74, v75
	global_load_dword v75, v[54:55], off offset:16
	s_waitcnt vmcnt(0)
	v_mul_f32_e32 v92, v75, v74
	v_lshl_add_u64 v[74:75], v[40:41], 0, s[84:85]
	v_lshl_add_u64 v[86:87], v[74:75], 0, s[78:79]
	v_add_co_u32_e32 v74, vcc, s25, v74
	s_nop 1
	v_addc_co_u32_e32 v75, vcc, 0, v75, vcc
	global_load_dwordx4 v[74:77], v[74:75], off
	s_nop 0
	global_load_dwordx4 v[78:81], v[86:87], off offset:32
	global_load_dwordx4 v[82:85], v[86:87], off offset:48
	s_nop 0
	global_load_dwordx4 v[86:89], v[86:87], off offset:16
	s_waitcnt vmcnt(3)
	v_mov_b32_e32 v90, v75
	v_mov_b32_e32 v91, v76
	v_mov_b32_e32 v75, v77
	s_waitcnt vmcnt(0)
	v_mov_b32_e32 v76, v87
	v_mov_b32_e32 v87, v89
	v_pk_mul_f32 v[74:75], v[20:21], v[74:75]
	v_mov_b32_e32 v77, v88
	v_pk_mul_f32 v[86:87], v[24:25], v[86:87]
	v_pk_fma_f32 v[74:75], v[22:23], v[90:91], v[74:75]
	v_pk_fma_f32 v[76:77], v[26:27], v[76:77], v[86:87]
	v_add_f32_e32 v74, v74, v75
	v_mul_f32_e32 v75, v12, v82
	v_mul_f32_e32 v82, v70, v83
	v_pk_add_f32 v[76:77], v[76:77], v[76:77] op_sel:[0,1] op_sel_hi:[1,0]
	v_add_f32_e32 v74, 0, v74
	v_mov_b32_e32 v77, v82
	v_pk_add_f32 v[74:75], v[74:75], v[76:77]
	v_mul_f32_e32 v76, v29, v79
	v_pk_fma_f32 v[76:77], v[28:29], v[78:79], v[76:77] op_sel_hi:[1,1,0]
	v_mul_f32_e32 v78, v31, v81
	v_mul_f32_e32 v83, v71, v84
	v_mul_f32_e32 v84, v72, v85
	v_pk_fma_f32 v[78:79], v[30:31], v[80:81], v[78:79] op_sel_hi:[1,1,0]
	v_mov_b32_e32 v77, v83
	v_mov_b32_e32 v79, v84
	v_pk_add_f32 v[76:77], v[76:77], v[78:79]
	s_nop 0
	v_pk_add_f32 v[74:75], v[74:75], v[76:77]
	s_nop 0
	v_add_f32_e32 v74, v74, v75
	global_load_dword v75, v[54:55], off offset:24
	s_waitcnt vmcnt(0)
	v_mul_f32_e32 v74, v75, v74
	ds_write2_b32 v73, v92, v74 offset0:132 offset1:198
	v_lshl_add_u64 v[74:75], v[38:39], 0, s[84:85]
	v_lshl_add_u64 v[86:87], v[74:75], 0, s[78:79]
	v_add_co_u32_e32 v74, vcc, s25, v74
	s_nop 1
	v_addc_co_u32_e32 v75, vcc, 0, v75, vcc
	global_load_dwordx4 v[74:77], v[74:75], off
	s_nop 0
	global_load_dwordx4 v[78:81], v[86:87], off offset:32
	global_load_dwordx4 v[82:85], v[86:87], off offset:48
	s_nop 0
	global_load_dwordx4 v[86:89], v[86:87], off offset:16
	s_waitcnt vmcnt(3)
	v_mov_b32_e32 v90, v75
	v_mov_b32_e32 v91, v76
	v_mov_b32_e32 v75, v77
	s_waitcnt vmcnt(0)
	v_mov_b32_e32 v76, v87
	v_mov_b32_e32 v87, v89
	v_pk_mul_f32 v[74:75], v[20:21], v[74:75]
	v_mov_b32_e32 v77, v88
	v_pk_mul_f32 v[86:87], v[24:25], v[86:87]
	v_pk_fma_f32 v[74:75], v[22:23], v[90:91], v[74:75]
	v_pk_fma_f32 v[76:77], v[26:27], v[76:77], v[86:87]
	v_add_f32_e32 v74, v74, v75
	v_mul_f32_e32 v75, v12, v82
	v_mul_f32_e32 v82, v70, v83
	v_pk_add_f32 v[76:77], v[76:77], v[76:77] op_sel:[0,1] op_sel_hi:[1,0]
	v_add_f32_e32 v74, 0, v74
	v_mov_b32_e32 v77, v82
	v_pk_add_f32 v[74:75], v[74:75], v[76:77]
	v_mul_f32_e32 v76, v29, v79
	v_pk_fma_f32 v[76:77], v[28:29], v[78:79], v[76:77] op_sel_hi:[1,1,0]
	v_mul_f32_e32 v78, v31, v81
	v_mul_f32_e32 v83, v71, v84
	v_mul_f32_e32 v84, v72, v85
	v_pk_fma_f32 v[78:79], v[30:31], v[80:81], v[78:79] op_sel_hi:[1,1,0]
	v_mov_b32_e32 v77, v83
	v_mov_b32_e32 v79, v84
	v_pk_add_f32 v[76:77], v[76:77], v[78:79]
	s_nop 0
	v_pk_add_f32 v[74:75], v[74:75], v[76:77]
	s_nop 0
	v_add_f32_e32 v74, v74, v75
	global_load_dword v75, v[54:55], off offset:32
	s_waitcnt vmcnt(0)
; __device__ __forceinline__ void fold_item(const float* Win, const float* wgg, const float* kgain, bf16_t* WT, int k0, int j0, int n_dst0, LAS float* scr, int lane) {
;     ...
;     for (int i = 0; i < 32; ++i) { const int kk = 2 * i + (lane >> 5); const f32x4* wr = (const f32x4*)(Win + (size_t)(k0 + kk) * NIN + C_GLR); float s = 0.f;
; #pragma unroll
;         for (int r4 = 0; r4 < GR / 4; ++r4) { const f32x4 x = wr[r4]; s += (x[0] * wg[4 * r4] + x[1] * wg[4 * r4 + 1]) + (x[2] * wg[4 * r4 + 2] + x[3] * wg[4 * r4 + 3]); }
;         scr[kk * 33 + (lane & 31)] = s * kgain[k0 + kk]; }
	v_mul_f32_e32 v92, v75, v74
	v_lshl_add_u64 v[74:75], v[36:37], 0, s[84:85]
	v_lshl_add_u64 v[86:87], v[74:75], 0, s[78:79]
	v_add_co_u32_e32 v74, vcc, s25, v74
	s_nop 1
	v_addc_co_u32_e32 v75, vcc, 0, v75, vcc
	global_load_dwordx4 v[74:77], v[74:75], off
	s_nop 0
	global_load_dwordx4 v[78:81], v[86:87], off offset:32
	global_load_dwordx4 v[82:85], v[86:87], off offset:48
	s_nop 0
	global_load_dwordx4 v[86:89], v[86:87], off offset:16
	s_waitcnt vmcnt(3)
	v_mov_b32_e32 v90, v75
	v_mov_b32_e32 v91, v76
	v_mov_b32_e32 v75, v77
	s_waitcnt vmcnt(0)
	v_mov_b32_e32 v76, v87
	v_mov_b32_e32 v87, v89
	v_pk_mul_f32 v[74:75], v[20:21], v[74:75]
	v_mov_b32_e32 v77, v88
	v_pk_mul_f32 v[86:87], v[24:25], v[86:87]
	v_pk_fma_f32 v[74:75], v[22:23], v[90:91], v[74:75]
	v_pk_fma_f32 v[76:77], v[26:27], v[76:77], v[86:87]
	v_add_f32_e32 v74, v74, v75
	v_mul_f32_e32 v75, v12, v82
	v_mul_f32_e32 v82, v70, v83
	v_pk_add_f32 v[76:77], v[76:77], v[76:77] op_sel:[0,1] op_sel_hi:[1,0]
	v_add_f32_e32 v74, 0, v74
	v_mov_b32_e32 v77, v82
	v_pk_add_f32 v[74:75], v[74:75], v[76:77]
	v_mul_f32_e32 v76, v29, v79
	v_pk_fma_f32 v[76:77], v[28:29], v[78:79], v[76:77] op_sel_hi:[1,1,0]
	v_mul_f32_e32 v78, v31, v81
	v_mul_f32_e32 v83, v71, v84
	v_mul_f32_e32 v84, v72, v85
	v_pk_fma_f32 v[78:79], v[30:31], v[80:81], v[78:79] op_sel_hi:[1,1,0]
	v_mov_b32_e32 v77, v83
	v_mov_b32_e32 v79, v84
	v_pk_add_f32 v[76:77], v[76:77], v[78:79]
	s_nop 0
	v_pk_add_f32 v[74:75], v[74:75], v[76:77]
	v_lshl_add_u64 v[76:77], v[34:35], 0, s[84:85]
	v_add_f32_e32 v74, v74, v75
	global_load_dword v75, v[54:55], off offset:40
	v_lshl_add_u64 v[88:89], v[76:77], 0, s[78:79]
	v_add_co_u32_e32 v76, vcc, s25, v76
	s_waitcnt vmcnt(0)
	v_mul_f32_e32 v75, v75, v74
	v_add_u32_e32 v74, 0x400, v73
	ds_write2_b32 v74, v92, v75 offset0:8 offset1:74
	v_addc_co_u32_e32 v77, vcc, 0, v77, vcc
	global_load_dwordx4 v[76:79], v[76:77], off
	s_nop 0
	global_load_dwordx4 v[80:83], v[88:89], off offset:32
	global_load_dwordx4 v[84:87], v[88:89], off offset:48
	s_nop 0
	global_load_dwordx4 v[88:91], v[88:89], off offset:16
	v_add_u32_e32 v73, 0x840, v73
	s_waitcnt vmcnt(3)
	v_mov_b32_e32 v92, v77
	v_mov_b32_e32 v77, v79
	v_mov_b32_e32 v93, v78
	v_pk_mul_f32 v[76:77], v[20:21], v[76:77]
	s_waitcnt vmcnt(0)
	v_mov_b32_e32 v78, v89
	v_mov_b32_e32 v89, v91
	v_pk_fma_f32 v[76:77], v[22:23], v[92:93], v[76:77]
	v_mov_b32_e32 v79, v90
	v_pk_mul_f32 v[88:89], v[24:25], v[88:89]
	v_add_f32_e32 v75, v76, v77
	v_pk_fma_f32 v[78:79], v[26:27], v[78:79], v[88:89]
	v_add_f32_e32 v76, 0, v75
	v_mul_f32_e32 v75, v70, v85
	v_pk_add_f32 v[78:79], v[78:79], v[78:79] op_sel:[0,1] op_sel_hi:[1,0]
	v_mul_f32_e32 v77, v12, v84
	v_mov_b32_e32 v79, v75
	v_pk_add_f32 v[76:77], v[76:77], v[78:79]
	v_mul_f32_e32 v78, v29, v81
	v_pk_fma_f32 v[78:79], v[28:29], v[80:81], v[78:79] op_sel_hi:[1,1,0]
	v_mul_f32_e32 v80, v31, v83
	v_mul_f32_e32 v84, v71, v86
	v_mul_f32_e32 v85, v72, v87
	v_pk_fma_f32 v[80:81], v[30:31], v[82:83], v[80:81] op_sel_hi:[1,1,0]
	v_mov_b32_e32 v79, v84
	v_mov_b32_e32 v81, v85
	v_pk_add_f32 v[78:79], v[78:79], v[80:81]
	s_nop 0
	v_pk_add_f32 v[76:77], v[76:77], v[78:79]
	s_nop 0
	v_add_f32_e32 v75, v76, v77
	global_load_dword v76, v[54:55], off offset:48
	s_waitcnt vmcnt(0)
	v_mul_f32_e32 v75, v76, v75
	v_lshl_add_u64 v[76:77], v[32:33], 0, s[84:85]
	v_lshl_add_u64 v[88:89], v[76:77], 0, s[78:79]
	v_add_co_u32_e32 v76, vcc, s25, v76
	s_add_u32 s84, s84, 0xb0400
	s_nop 0
	v_addc_co_u32_e32 v77, vcc, 0, v77, vcc
	global_load_dwordx4 v[76:79], v[76:77], off
	s_nop 0
	global_load_dwordx4 v[80:83], v[88:89], off offset:32
	global_load_dwordx4 v[84:87], v[88:89], off offset:48
	s_nop 0
	global_load_dwordx4 v[88:91], v[88:89], off offset:16
	s_addc_u32 s85, s85, 0
	global_load_dword v54, v[54:55], off offset:56
	s_cmp_lg_u32 s84, 0x2c1000
	s_waitcnt vmcnt(4)
	v_mov_b32_e32 v92, v77
	v_mov_b32_e32 v93, v78
	v_mov_b32_e32 v77, v79
	s_waitcnt vmcnt(1)
	v_mov_b32_e32 v78, v89
	v_mov_b32_e32 v89, v91
	v_pk_mul_f32 v[76:77], v[20:21], v[76:77]
	v_mov_b32_e32 v79, v90
	v_pk_mul_f32 v[88:89], v[24:25], v[88:89]
	v_pk_fma_f32 v[76:77], v[22:23], v[92:93], v[76:77]
	v_pk_fma_f32 v[78:79], v[26:27], v[78:79], v[88:89]
	v_add_f32_e32 v76, v76, v77
	v_mul_f32_e32 v77, v12, v84
	v_mul_f32_e32 v84, v70, v85
	v_pk_add_f32 v[78:79], v[78:79], v[78:79] op_sel:[0,1] op_sel_hi:[1,0]
	v_add_f32_e32 v76, 0, v76
	v_mov_b32_e32 v79, v84
	v_pk_add_f32 v[76:77], v[76:77], v[78:79]
	v_mul_f32_e32 v78, v29, v81
	v_pk_fma_f32 v[78:79], v[28:29], v[80:81], v[78:79] op_sel_hi:[1,1,0]
	v_mul_f32_e32 v80, v31, v83
	v_mul_f32_e32 v85, v71, v86
	v_mul_f32_e32 v86, v72, v87
	v_pk_fma_f32 v[80:81], v[30:31], v[82:83], v[80:81] op_sel_hi:[1,1,0]
	v_mov_b32_e32 v79, v85
	v_mov_b32_e32 v81, v86
	v_pk_add_f32 v[78:79], v[78:79], v[80:81]
	s_nop 0
	v_pk_add_f32 v[76:77], v[76:77], v[78:79]
	s_nop 0
	v_add_f32_e32 v76, v76, v77
	s_waitcnt vmcnt(0)
	v_mul_f32_e32 v54, v54, v76
	ds_write2_b32 v74, v75, v54 offset0:140 offset1:206
	s_cbranch_scc1 .LBB0_47
; #define LAS __attribute__((address_space(3)))
; __device__ __forceinline__ unsigned pk2(float lo, float hi) { return pg8::cvt_pk_bf16(lo, hi); }
; __device__ __forceinline__ void fold_item(const float* Win, const float* wgg, const float* kgain, bf16_t* WT, int k0, int j0, int n_dst0, LAS float* scr, int lane) {
;     ...
;     asm volatile("s_waitcnt lgkmcnt(0)" ::: "memory");
;     const int c = lane & 7;
; #pragma unroll
;     for (int j = 0; j < 4; ++j) { const int n = (lane >> 3) + 8 * j; const LAS float* s = scr + (8 * c) * 33 + n;
;         u32x4 o; o.x = pk2(s[0 * 33], s[1 * 33]); o.y = pk2(s[2 * 33], s[3 * 33]); o.z = pk2(s[4 * 33], s[5 * 33]); o.w = pk2(s[6 * 33], s[7 * 33]);
;         *(u32x4*)(WT + (size_t)(n_dst0 + n) * D + k0 + 8 * c) = o; }
;     asm volatile("s_waitcnt lgkmcnt(0)" ::: "memory");
	s_waitcnt lgkmcnt(0)
	ds_read2_b32 v[20:21], v11 offset0:33 offset1:41
	ds_read2_b32 v[22:23], v11 offset1:8
	ds_read2_b32 v[24:25], v11 offset0:66 offset1:74
	ds_read2_b32 v[26:27], v11 offset0:99 offset1:107
	ds_read2_b32 v[28:29], v11 offset0:132 offset1:140
	ds_read2_b32 v[30:31], v11 offset0:165 offset1:173
	ds_read2_b32 v[32:33], v11 offset0:198 offset1:206
	ds_read2_b32 v[34:35], v11 offset0:231 offset1:239
	v_lshl_add_u64 v[16:17], v[18:19], 1, v[16:17]
	v_lshlrev_b32_e32 v12, 1, v14
	v_lshl_add_u64 v[36:37], v[16:17], 0, v[12:13]
	v_or_b32_e32 v12, v69, v7
	v_lshlrev_b32_e32 v12, 12, v12
	s_waitcnt lgkmcnt(6)
	v_cvt_pk_bf16_f32 v16, v22, v20
	s_waitcnt lgkmcnt(4)
	v_cvt_pk_bf16_f32 v17, v24, v26
	s_waitcnt lgkmcnt(2)
	v_cvt_pk_bf16_f32 v18, v28, v30
	s_waitcnt lgkmcnt(0)
	v_cvt_pk_bf16_f32 v19, v32, v34
	v_lshl_add_u64 v[38:39], v[36:37], 0, v[12:13]
	global_store_dwordx4 v[38:39], v[16:19], off
	v_or_b32_e32 v12, v69, v15
	v_lshlrev_b32_e32 v12, 12, v12
	v_cvt_pk_bf16_f32 v16, v23, v21
	v_cvt_pk_bf16_f32 v17, v25, v27
	v_cvt_pk_bf16_f32 v18, v29, v31
	v_cvt_pk_bf16_f32 v19, v33, v35
	ds_read2_b32 v[22:23], v11 offset0:49 offset1:57
	ds_read2_b32 v[24:25], v11 offset0:16 offset1:24
	ds_read2_b32 v[26:27], v11 offset0:82 offset1:90
	ds_read2_b32 v[28:29], v11 offset0:115 offset1:123
	ds_read2_b32 v[30:31], v11 offset0:148 offset1:156
	ds_read2_b32 v[32:33], v11 offset0:181 offset1:189
	ds_read2_b32 v[34:35], v11 offset0:214 offset1:222
	ds_read2_b32 v[38:39], v11 offset0:247 offset1:255
	v_lshl_add_u64 v[20:21], v[36:37], 0, v[12:13]
	v_or_b32_e32 v12, v69, v56
	v_lshlrev_b32_e32 v12, 12, v12
	global_store_dwordx4 v[20:21], v[16:19], off
	v_lshl_add_u64 v[20:21], v[36:37], 0, v[12:13]
	v_or_b32_e32 v12, v69, v57
	s_waitcnt lgkmcnt(6)
	v_cvt_pk_bf16_f32 v16, v24, v22
	s_waitcnt lgkmcnt(4)
	v_cvt_pk_bf16_f32 v17, v26, v28
	s_waitcnt lgkmcnt(2)
	v_cvt_pk_bf16_f32 v18, v30, v32
	s_waitcnt lgkmcnt(0)
	v_cvt_pk_bf16_f32 v19, v34, v38
	v_lshlrev_b32_e32 v12, 12, v12
	global_store_dwordx4 v[20:21], v[16:19], off
	v_lshl_add_u64 v[20:21], v[36:37], 0, v[12:13]
	s_nop 0
	v_cvt_pk_bf16_f32 v16, v25, v23
	v_cvt_pk_bf16_f32 v17, v27, v29
	v_cvt_pk_bf16_f32 v18, v31, v33
	v_cvt_pk_bf16_f32 v19, v35, v39
	global_store_dwordx4 v[20:21], v[16:19], off
	s_waitcnt lgkmcnt(0)
	s_branch .LBB0_10
